# GEMM K-loops: per-accumulator k-steps back-to-back (n-major snake), end-of-segment barrier moved up 2 MFMAs, redundant setprio/waitcnt removed
# speedup vs baseline: 1.0153x; 1.0006x over previous
; #define PG8_STAGE(bufoff, gbase, voff) do { _Pragma("unroll") for (int _i = 0; _i < 2; ++_i) \
;         __builtin_amdgcn_global_load_lds((const unsigned*)((const char*)(gbase) + (voff)[_i]), (PG8_LAS unsigned*)(lds + (bufoff) + ldsw + _i * 8192), 16, 0, 0); } while (0)
; #define PG8_LDA(dst, b, h) do { _Pragma("unroll") for (int m = 0; m < 4; ++m) _Pragma("unroll") for (int k = 0; k < 2; ++k) dst[m][k] = *(const PG8_LAS bf16x8*)(lds + PG8_SA(b, h) + aoff + m * 2048 + k * 1024); } while (0)
; #define PG8_LDB(dst, b, h) do { _Pragma("unroll") for (int n = 0; n < 2; ++n) _Pragma("unroll") for (int k = 0; k < 2; ++k) dst[n][k] = *(const PG8_LAS bf16x8*)(lds + PG8_SB(b, h) + boff + n * 2048 + k * 1024); } while (0)
; #define PG8_MMA(ai, bj, At, Bt) do { __builtin_amdgcn_s_setprio(1); _Pragma("unroll") for (int m = 0; m < 4; ++m) _Pragma("unroll") for (int n = 0; n < 2; ++n) _Pragma("unroll") for (int k = 0; k < 2; ++k) \
;         acc[ai][bj][m][n] = __builtin_amdgcn_mfma_f32_16x16x32_bf16(Bt[n][k], At[m][k], acc[ai][bj][m][n], 0, 0, 0); __builtin_amdgcn_s_setprio(0); } while (0)
; #define PG8_WAIT_V(n) asm volatile("s_waitcnt vmcnt(" #n ")" ::: "memory")
; #define PG8_BAR __builtin_amdgcn_s_barrier()
; template <class Epi, class Sched, bool ALIGN_EPI = false, bool SP2 = false>
; __device__ __forceinline__ void gemm_phase(PG8_LAS unsigned char* lds, const Gemm g, const Sched& S, const Epi& E) {
;     ...
;         for (int t = 0; t < nt; t += 2) {
;             const bool last = (t == nt - 2);
;             const char* a1 = cA + (size_t)(t + 1) * kstep;
;             const char* a2 = last ? nA : cA + (size_t)(t + 2) * kstep; const char* b2 = last ? nB : cB + (size_t)(t + 2) * kstep;
;             const char* a3 = a2 + kstep; const char* b3 = b2 + kstep;
;             if (last && has_next) S.a_ready(nxt);
;             if constexpr (SP2) {
;             PG8_LDB(B0, 0, 0); PG8_LDB(B1, 0, 1); PG8_SCHED; PG8_LDA(At, 0, 0); PG8_STAGE(PG8_SA(1, 1), a1 + hstep, voffA);
;             PG8_WAIT_V(8); PG8_WAIT_L(0); PG8_BAR; PG8_MMA(0, 0, At, B0); PG8_MMA(0, 1, At, B1); PG8_BAR; PG8_SCHED;
;             PG8_LDA(At, 0, 1); PG8_STAGE(PG8_SB(0, 0), b2, voffB); PG8_STAGE(PG8_SB(0, 1), b2 + hstep, voffB); PG8_STAGE(PG8_SA(0, 0), a2, voffA);
;             PG8_WAIT_V(8); PG8_WAIT_L(0); PG8_BAR; PG8_MMA(1, 0, At, B0); PG8_MMA(1, 1, At, B1); PG8_BAR; PG8_SCHED;
.LBB0_102:
	ds_read_b128 v[160:163], v155
	ds_read_b128 v[164:167], v155 offset:1024
	ds_read_b128 v[168:171], v155 offset:2048
	ds_read_b128 v[172:175], v155 offset:3072
	ds_read_b128 v[176:179], v157
	ds_read_b128 v[180:183], v157 offset:1024
	ds_read_b128 v[184:187], v157 offset:2048
	ds_read_b128 v[188:191], v157 offset:3072
	s_add_u32 s62, s74, 0xfff80080
	s_addc_u32 s63, s75, -1
	s_cmp_eq_u32 s90, 28
	s_cselect_b32 s79, s10, s63
	s_cselect_b32 s78, s11, s62
	s_cselect_b32 s77, s51, s89
	s_cselect_b32 s76, s55, s88
	v_lshl_add_u64 v[224:225], s[74:75], 0, v[138:139]
	s_add_i32 m0, s61, 0xc000
	ds_read_b128 v[192:195], v159
	ds_read_b128 v[196:199], v159 offset:1024
	ds_read_b128 v[200:203], v159 offset:2048
	ds_read_b128 v[204:207], v159 offset:3072
	ds_read_b128 v[208:211], v159 offset:4096
	ds_read_b128 v[212:215], v159 offset:5120
	ds_read_b128 v[216:219], v159 offset:6144
	ds_read_b128 v[220:223], v159 offset:7168
	global_load_lds_dwordx4 v[224:225], off
	v_lshl_add_u64 v[224:225], s[74:75], 0, v[140:141]
	s_add_i32 m0, s61, 0xe000
	s_nop 0
	global_load_lds_dwordx4 v[224:225], off
	s_waitcnt vmcnt(8)
	s_waitcnt lgkmcnt(0)
	s_setprio 1
	s_barrier
	v_mfma_f32_16x16x32_bf16 v[124:127], v[160:163], v[192:195], v[124:127]
	v_mfma_f32_16x16x32_bf16 v[124:127], v[164:167], v[196:199], v[124:127]
	v_mfma_f32_16x16x32_bf16 v[108:111], v[160:163], v[200:203], v[108:111]
	v_mfma_f32_16x16x32_bf16 v[108:111], v[164:167], v[204:207], v[108:111]
	v_mfma_f32_16x16x32_bf16 v[92:95], v[160:163], v[208:211], v[92:95]
	v_mfma_f32_16x16x32_bf16 v[92:95], v[164:167], v[212:215], v[92:95]
	v_mfma_f32_16x16x32_bf16 v[76:79], v[160:163], v[216:219], v[76:79]
	v_mfma_f32_16x16x32_bf16 v[76:79], v[164:167], v[220:223], v[76:79]
	v_mfma_f32_16x16x32_bf16 v[72:75], v[168:171], v[216:219], v[72:75]
	v_mfma_f32_16x16x32_bf16 v[72:75], v[172:175], v[220:223], v[72:75]
	v_mfma_f32_16x16x32_bf16 v[88:91], v[168:171], v[208:211], v[88:91]
	v_mfma_f32_16x16x32_bf16 v[88:91], v[172:175], v[212:215], v[88:91]
	v_mfma_f32_16x16x32_bf16 v[104:107], v[168:171], v[200:203], v[104:107]
	v_mfma_f32_16x16x32_bf16 v[104:107], v[172:175], v[204:207], v[104:107]
	v_mfma_f32_16x16x32_bf16 v[120:123], v[168:171], v[192:195], v[120:123]
	v_mfma_f32_16x16x32_bf16 v[120:123], v[172:175], v[196:199], v[120:123]
	v_mfma_f32_16x16x32_bf16 v[116:119], v[176:179], v[192:195], v[116:119]
	v_mfma_f32_16x16x32_bf16 v[116:119], v[180:183], v[196:199], v[116:119]
	v_mfma_f32_16x16x32_bf16 v[100:103], v[176:179], v[200:203], v[100:103]
	v_mfma_f32_16x16x32_bf16 v[100:103], v[180:183], v[204:207], v[100:103]
	v_mfma_f32_16x16x32_bf16 v[84:87], v[176:179], v[208:211], v[84:87]
	v_mfma_f32_16x16x32_bf16 v[84:87], v[180:183], v[212:215], v[84:87]
	v_mfma_f32_16x16x32_bf16 v[68:71], v[176:179], v[216:219], v[68:71]
	v_mfma_f32_16x16x32_bf16 v[68:71], v[180:183], v[220:223], v[68:71]
	v_mfma_f32_16x16x32_bf16 v[64:67], v[184:187], v[216:219], v[64:67]
	v_mfma_f32_16x16x32_bf16 v[64:67], v[188:191], v[220:223], v[64:67]
	v_mfma_f32_16x16x32_bf16 v[80:83], v[184:187], v[208:211], v[80:83]
	v_mfma_f32_16x16x32_bf16 v[80:83], v[188:191], v[212:215], v[80:83]
	v_mfma_f32_16x16x32_bf16 v[96:99], v[184:187], v[200:203], v[96:99]
	v_mfma_f32_16x16x32_bf16 v[96:99], v[188:191], v[204:207], v[96:99]
	s_setprio 2
	s_barrier
	v_mfma_f32_16x16x32_bf16 v[112:115], v[184:187], v[192:195], v[112:115]
	v_mfma_f32_16x16x32_bf16 v[112:115], v[188:191], v[196:199], v[112:115]
	s_setprio 0
	s_add_i32 s62, s84, s35
	v_lshl_add_u64 v[224:225], s[76:77], 0, v[130:131]
	s_mov_b32 m0, s62
	ds_read_b128 v[192:195], v159 offset:16384
	ds_read_b128 v[196:199], v159 offset:17408
	ds_read_b128 v[200:203], v159 offset:18432
	ds_read_b128 v[204:207], v159 offset:19456
	ds_read_b128 v[208:211], v159 offset:20480
	ds_read_b128 v[212:215], v159 offset:21504
	ds_read_b128 v[216:219], v159 offset:22528
	ds_read_b128 v[220:223], v159 offset:23552
	global_load_lds_dwordx4 v[224:225], off
	s_add_i32 m0, s62, 0x2000
	s_add_u32 s92, s76, 0x80000
	v_lshl_add_u64 v[226:227], s[76:77], 0, v[134:135]
	s_addc_u32 s93, s77, 0
	s_add_i32 s62, s85, s35
	global_load_lds_dwordx4 v[226:227], off
	v_lshl_add_u64 v[228:229], s[92:93], 0, v[130:131]
	s_mov_b32 m0, s62
	v_lshl_add_u64 v[230:231], s[78:79], 0, v[132:133]
	global_load_lds_dwordx4 v[228:229], off
	v_lshl_add_u64 v[228:229], s[92:93], 0, v[134:135]
	s_add_i32 m0, s62, 0x2000
	s_nop 0
	global_load_lds_dwordx4 v[228:229], off
	v_lshl_add_u64 v[228:229], s[78:79], 0, v[128:129]
	s_mov_b32 m0, s61
	s_nop 0
	global_load_lds_dwordx4 v[228:229], off
	s_mov_b32 m0, s65
	s_nop 0
	global_load_lds_dwordx4 v[230:231], off
	s_waitcnt vmcnt(8)
	s_waitcnt lgkmcnt(0)
	s_setprio 1
	s_barrier
; #define PG8_STAGE(bufoff, gbase, voff) do { _Pragma("unroll") for (int _i = 0; _i < 2; ++_i) \
;         __builtin_amdgcn_global_load_lds((const unsigned*)((const char*)(gbase) + (voff)[_i]), (PG8_LAS unsigned*)(lds + (bufoff) + ldsw + _i * 8192), 16, 0, 0); } while (0)
; #define PG8_LDA(dst, b, h) do { _Pragma("unroll") for (int m = 0; m < 4; ++m) _Pragma("unroll") for (int k = 0; k < 2; ++k) dst[m][k] = *(const PG8_LAS bf16x8*)(lds + PG8_SA(b, h) + aoff + m * 2048 + k * 1024); } while (0)
; #define PG8_LDB(dst, b, h) do { _Pragma("unroll") for (int n = 0; n < 2; ++n) _Pragma("unroll") for (int k = 0; k < 2; ++k) dst[n][k] = *(const PG8_LAS bf16x8*)(lds + PG8_SB(b, h) + boff + n * 2048 + k * 1024); } while (0)
; #define PG8_MMA(ai, bj, At, Bt) do { __builtin_amdgcn_s_setprio(1); _Pragma("unroll") for (int m = 0; m < 4; ++m) _Pragma("unroll") for (int n = 0; n < 2; ++n) _Pragma("unroll") for (int k = 0; k < 2; ++k) \
;         acc[ai][bj][m][n] = __builtin_amdgcn_mfma_f32_16x16x32_bf16(Bt[n][k], At[m][k], acc[ai][bj][m][n], 0, 0, 0); __builtin_amdgcn_s_setprio(0); } while (0)
; #define PG8_WAIT_V(n) asm volatile("s_waitcnt vmcnt(" #n ")" ::: "memory")
; #define PG8_WAIT_L(n) asm volatile("s_waitcnt lgkmcnt(" #n ")" ::: "memory")
; #define PG8_BAR __builtin_amdgcn_s_barrier()
; #define PG8_SCHED __builtin_amdgcn_sched_barrier(0)
; template <class Epi, class Sched, bool ALIGN_EPI = false, bool SP2 = false>
; __device__ __forceinline__ void gemm_phase(PG8_LAS unsigned char* lds, const Gemm g, const Sched& S, const Epi& E) {
;     ...
;             PG8_WAIT_V(8); PG8_WAIT_L(0); PG8_BAR; PG8_MMA(1, 0, At, B0); PG8_MMA(1, 1, At, B1); PG8_BAR; PG8_SCHED;
;             PG8_LDB(B0, 1, 0); PG8_LDB(B1, 1, 1); PG8_SCHED; PG8_LDA(At, 1, 0); PG8_STAGE(PG8_SA(0, 1), a2 + hstep, voffA);
;             PG8_WAIT_V(8); PG8_WAIT_L(0); PG8_BAR; PG8_MMA(0, 0, At, B0); PG8_MMA(0, 1, At, B1); PG8_BAR; PG8_SCHED;
	v_mfma_f32_16x16x32_bf16 v[60:63], v[160:163], v[192:195], v[60:63]
	v_mfma_f32_16x16x32_bf16 v[60:63], v[164:167], v[196:199], v[60:63]
	v_mfma_f32_16x16x32_bf16 v[44:47], v[160:163], v[200:203], v[44:47]
	v_mfma_f32_16x16x32_bf16 v[44:47], v[164:167], v[204:207], v[44:47]
	v_mfma_f32_16x16x32_bf16 v[28:31], v[160:163], v[208:211], v[28:31]
	v_mfma_f32_16x16x32_bf16 v[28:31], v[164:167], v[212:215], v[28:31]
	v_mfma_f32_16x16x32_bf16 v[12:15], v[160:163], v[216:219], v[12:15]
	v_mfma_f32_16x16x32_bf16 v[12:15], v[164:167], v[220:223], v[12:15]
	v_mfma_f32_16x16x32_bf16 v[8:11], v[168:171], v[216:219], v[8:11]
	v_mfma_f32_16x16x32_bf16 v[8:11], v[172:175], v[220:223], v[8:11]
	v_mfma_f32_16x16x32_bf16 v[24:27], v[168:171], v[208:211], v[24:27]
	v_mfma_f32_16x16x32_bf16 v[24:27], v[172:175], v[212:215], v[24:27]
	v_mfma_f32_16x16x32_bf16 v[40:43], v[168:171], v[200:203], v[40:43]
	v_mfma_f32_16x16x32_bf16 v[40:43], v[172:175], v[204:207], v[40:43]
	v_mfma_f32_16x16x32_bf16 v[56:59], v[168:171], v[192:195], v[56:59]
	v_mfma_f32_16x16x32_bf16 v[56:59], v[172:175], v[196:199], v[56:59]
	v_mfma_f32_16x16x32_bf16 v[52:55], v[176:179], v[192:195], v[52:55]
	v_mfma_f32_16x16x32_bf16 v[52:55], v[180:183], v[196:199], v[52:55]
	v_mfma_f32_16x16x32_bf16 v[36:39], v[176:179], v[200:203], v[36:39]
	v_mfma_f32_16x16x32_bf16 v[36:39], v[180:183], v[204:207], v[36:39]
	v_mfma_f32_16x16x32_bf16 v[20:23], v[176:179], v[208:211], v[20:23]
	v_mfma_f32_16x16x32_bf16 v[20:23], v[180:183], v[212:215], v[20:23]
	v_mfma_f32_16x16x32_bf16 v[4:7], v[176:179], v[216:219], v[4:7]
	v_mfma_f32_16x16x32_bf16 v[4:7], v[180:183], v[220:223], v[4:7]
	v_mfma_f32_16x16x32_bf16 v[0:3], v[184:187], v[216:219], v[0:3]
	v_mfma_f32_16x16x32_bf16 v[0:3], v[188:191], v[220:223], v[0:3]
	v_mfma_f32_16x16x32_bf16 v[16:19], v[184:187], v[208:211], v[16:19]
	v_mfma_f32_16x16x32_bf16 v[16:19], v[188:191], v[212:215], v[16:19]
	v_mfma_f32_16x16x32_bf16 v[32:35], v[184:187], v[200:203], v[32:35]
	v_mfma_f32_16x16x32_bf16 v[32:35], v[188:191], v[204:207], v[32:35]
	s_setprio 2
	s_barrier
	v_mfma_f32_16x16x32_bf16 v[48:51], v[184:187], v[192:195], v[48:51]
	v_mfma_f32_16x16x32_bf16 v[48:51], v[188:191], v[196:199], v[48:51]
	s_setprio 0
	s_add_i32 s62, 0, 0x18000
	s_add_i32 s63, 0, 0x1c000
	v_add_u32_e32 v172, s62, v147
	v_add_u32_e32 v188, s63, v147
	ds_read_b128 v[160:163], v172
	ds_read_b128 v[164:167], v172 offset:1024
	ds_read_b128 v[168:171], v172 offset:2048
	ds_read_b128 v[172:175], v172 offset:3072
	ds_read_b128 v[176:179], v188
	ds_read_b128 v[180:183], v188 offset:1024
	ds_read_b128 v[184:187], v188 offset:2048
	ds_read_b128 v[188:191], v188 offset:3072
	s_add_u32 s78, s78, 0x80000
	s_addc_u32 s79, s79, 0
	s_mov_b32 m0, s66
	v_lshl_add_u64 v[232:233], s[78:79], 0, v[128:129]
	ds_read_b128 v[192:195], v159 offset:32768
	ds_read_b128 v[196:199], v159 offset:33792
	ds_read_b128 v[200:203], v159 offset:34816
	ds_read_b128 v[204:207], v159 offset:35840
	ds_read_b128 v[208:211], v159 offset:36864
	ds_read_b128 v[212:215], v159 offset:37888
	ds_read_b128 v[216:219], v159 offset:38912
	ds_read_b128 v[220:223], v159 offset:39936
	global_load_lds_dwordx4 v[232:233], off
	v_lshl_add_u64 v[232:233], s[78:79], 0, v[132:133]
	s_mov_b32 m0, s67
	s_nop 0
	global_load_lds_dwordx4 v[232:233], off
	s_waitcnt vmcnt(8)
	s_waitcnt lgkmcnt(0)
	s_setprio 1
	s_barrier
	v_mfma_f32_16x16x32_bf16 v[124:127], v[160:163], v[192:195], v[124:127]
	v_mfma_f32_16x16x32_bf16 v[124:127], v[164:167], v[196:199], v[124:127]
	v_mfma_f32_16x16x32_bf16 v[108:111], v[160:163], v[200:203], v[108:111]
	v_mfma_f32_16x16x32_bf16 v[108:111], v[164:167], v[204:207], v[108:111]
	v_mfma_f32_16x16x32_bf16 v[92:95], v[160:163], v[208:211], v[92:95]
	v_mfma_f32_16x16x32_bf16 v[92:95], v[164:167], v[212:215], v[92:95]
	v_mfma_f32_16x16x32_bf16 v[76:79], v[160:163], v[216:219], v[76:79]
	v_mfma_f32_16x16x32_bf16 v[76:79], v[164:167], v[220:223], v[76:79]
	v_mfma_f32_16x16x32_bf16 v[72:75], v[168:171], v[216:219], v[72:75]
	v_mfma_f32_16x16x32_bf16 v[72:75], v[172:175], v[220:223], v[72:75]
	v_mfma_f32_16x16x32_bf16 v[88:91], v[168:171], v[208:211], v[88:91]
	v_mfma_f32_16x16x32_bf16 v[88:91], v[172:175], v[212:215], v[88:91]
	v_mfma_f32_16x16x32_bf16 v[104:107], v[168:171], v[200:203], v[104:107]
	v_mfma_f32_16x16x32_bf16 v[104:107], v[172:175], v[204:207], v[104:107]
	v_mfma_f32_16x16x32_bf16 v[120:123], v[168:171], v[192:195], v[120:123]
	v_mfma_f32_16x16x32_bf16 v[120:123], v[172:175], v[196:199], v[120:123]
	v_mfma_f32_16x16x32_bf16 v[116:119], v[176:179], v[192:195], v[116:119]
	v_mfma_f32_16x16x32_bf16 v[116:119], v[180:183], v[196:199], v[116:119]
	v_mfma_f32_16x16x32_bf16 v[100:103], v[176:179], v[200:203], v[100:103]
	v_mfma_f32_16x16x32_bf16 v[100:103], v[180:183], v[204:207], v[100:103]
	v_mfma_f32_16x16x32_bf16 v[84:87], v[176:179], v[208:211], v[84:87]
	v_mfma_f32_16x16x32_bf16 v[84:87], v[180:183], v[212:215], v[84:87]
	v_mfma_f32_16x16x32_bf16 v[68:71], v[176:179], v[216:219], v[68:71]
	v_mfma_f32_16x16x32_bf16 v[68:71], v[180:183], v[220:223], v[68:71]
	v_mfma_f32_16x16x32_bf16 v[64:67], v[184:187], v[216:219], v[64:67]
	v_mfma_f32_16x16x32_bf16 v[64:67], v[188:191], v[220:223], v[64:67]
	v_mfma_f32_16x16x32_bf16 v[80:83], v[184:187], v[208:211], v[80:83]
	v_mfma_f32_16x16x32_bf16 v[80:83], v[188:191], v[212:215], v[80:83]
	v_mfma_f32_16x16x32_bf16 v[96:99], v[184:187], v[200:203], v[96:99]
	v_mfma_f32_16x16x32_bf16 v[96:99], v[188:191], v[204:207], v[96:99]
	s_setprio 2
	s_barrier
; #define PG8_STAGE(bufoff, gbase, voff) do { _Pragma("unroll") for (int _i = 0; _i < 2; ++_i) \
;         __builtin_amdgcn_global_load_lds((const unsigned*)((const char*)(gbase) + (voff)[_i]), (PG8_LAS unsigned*)(lds + (bufoff) + ldsw + _i * 8192), 16, 0, 0); } while (0)
; #define PG8_LDA(dst, b, h) do { _Pragma("unroll") for (int m = 0; m < 4; ++m) _Pragma("unroll") for (int k = 0; k < 2; ++k) dst[m][k] = *(const PG8_LAS bf16x8*)(lds + PG8_SA(b, h) + aoff + m * 2048 + k * 1024); } while (0)
; #define PG8_MMA(ai, bj, At, Bt) do { __builtin_amdgcn_s_setprio(1); _Pragma("unroll") for (int m = 0; m < 4; ++m) _Pragma("unroll") for (int n = 0; n < 2; ++n) _Pragma("unroll") for (int k = 0; k < 2; ++k) \
;         acc[ai][bj][m][n] = __builtin_amdgcn_mfma_f32_16x16x32_bf16(Bt[n][k], At[m][k], acc[ai][bj][m][n], 0, 0, 0); __builtin_amdgcn_s_setprio(0); } while (0)
; #define PG8_WAIT_V(n) asm volatile("s_waitcnt vmcnt(" #n ")" ::: "memory")
; #define PG8_WAIT_L(n) asm volatile("s_waitcnt lgkmcnt(" #n ")" ::: "memory")
; #define PG8_BAR __builtin_amdgcn_s_barrier()
; #define PG8_SCHED __builtin_amdgcn_sched_barrier(0)
; template <class Epi, class Sched, bool ALIGN_EPI = false, bool SP2 = false>
; __device__ __forceinline__ void gemm_phase(PG8_LAS unsigned char* lds, const Gemm g, const Sched& S, const Epi& E) {
;     ...
;         for (int t = 0; t < nt; t += 2) {
;     ...
;             PG8_WAIT_V(8); PG8_WAIT_L(0); PG8_BAR; PG8_MMA(0, 0, At, B0); PG8_MMA(0, 1, At, B1); PG8_BAR; PG8_SCHED;
;             PG8_LDA(At, 1, 1); PG8_STAGE(PG8_SB(1, 0), b3, voffB); PG8_STAGE(PG8_SB(1, 1), b3 + hstep, voffB); PG8_STAGE(PG8_SA(1, 0), a3, voffA);
;             PG8_WAIT_V(8); PG8_WAIT_L(0); PG8_BAR; PG8_MMA(1, 0, At, B0); PG8_MMA(1, 1, At, B1); PG8_BAR; PG8_SCHED;
	v_mfma_f32_16x16x32_bf16 v[112:115], v[184:187], v[192:195], v[112:115]
	v_mfma_f32_16x16x32_bf16 v[112:115], v[188:191], v[196:199], v[112:115]
	s_setprio 0
	s_add_i32 s62, s62, s35
	v_lshl_add_u64 v[224:225], v[224:225], 0, s[18:19]
	s_mov_b32 m0, s62
	ds_read_b128 v[192:195], v159 offset:49152
	ds_read_b128 v[196:199], v159 offset:50176
	ds_read_b128 v[200:203], v159 offset:51200
	ds_read_b128 v[204:207], v159 offset:52224
	ds_read_b128 v[208:211], v159 offset:53248
	ds_read_b128 v[212:215], v159 offset:54272
	ds_read_b128 v[216:219], v159 offset:55296
	ds_read_b128 v[220:223], v159 offset:56320
	global_load_lds_dwordx4 v[224:225], off
	s_add_i32 m0, s62, 0x2000
	s_add_u32 s76, s76, 0x80080
	v_lshl_add_u64 v[224:225], v[226:227], 0, s[18:19]
	s_addc_u32 s77, s77, 0
	s_add_i32 s62, s63, s35
	global_load_lds_dwordx4 v[224:225], off
	v_lshl_add_u64 v[224:225], s[76:77], 0, v[130:131]
	s_mov_b32 m0, s62
	s_nop 0
	global_load_lds_dwordx4 v[224:225], off
	v_lshl_add_u64 v[224:225], s[76:77], 0, v[134:135]
	s_add_i32 m0, s62, 0x2000
	s_nop 0
	global_load_lds_dwordx4 v[224:225], off
	v_lshl_add_u64 v[224:225], v[228:229], 0, s[18:19]
	s_mov_b32 m0, s81
	s_nop 0
	global_load_lds_dwordx4 v[224:225], off
	v_lshl_add_u64 v[224:225], v[230:231], 0, s[18:19]
	s_mov_b32 m0, s82
	s_nop 0
	global_load_lds_dwordx4 v[224:225], off
	s_waitcnt vmcnt(8)
	s_waitcnt lgkmcnt(0)
	s_setprio 1
	s_barrier
	v_mfma_f32_16x16x32_bf16 v[60:63], v[160:163], v[192:195], v[60:63]
	v_mfma_f32_16x16x32_bf16 v[60:63], v[164:167], v[196:199], v[60:63]
	v_mfma_f32_16x16x32_bf16 v[44:47], v[160:163], v[200:203], v[44:47]
	v_mfma_f32_16x16x32_bf16 v[44:47], v[164:167], v[204:207], v[44:47]
	v_mfma_f32_16x16x32_bf16 v[28:31], v[160:163], v[208:211], v[28:31]
	v_mfma_f32_16x16x32_bf16 v[28:31], v[164:167], v[212:215], v[28:31]
	v_mfma_f32_16x16x32_bf16 v[12:15], v[160:163], v[216:219], v[12:15]
	v_mfma_f32_16x16x32_bf16 v[12:15], v[164:167], v[220:223], v[12:15]
	v_mfma_f32_16x16x32_bf16 v[8:11], v[168:171], v[216:219], v[8:11]
	v_mfma_f32_16x16x32_bf16 v[8:11], v[172:175], v[220:223], v[8:11]
	v_mfma_f32_16x16x32_bf16 v[24:27], v[168:171], v[208:211], v[24:27]
	v_mfma_f32_16x16x32_bf16 v[24:27], v[172:175], v[212:215], v[24:27]
	v_mfma_f32_16x16x32_bf16 v[40:43], v[168:171], v[200:203], v[40:43]
	v_mfma_f32_16x16x32_bf16 v[40:43], v[172:175], v[204:207], v[40:43]
	v_mfma_f32_16x16x32_bf16 v[56:59], v[168:171], v[192:195], v[56:59]
	v_mfma_f32_16x16x32_bf16 v[56:59], v[172:175], v[196:199], v[56:59]
	v_mfma_f32_16x16x32_bf16 v[52:55], v[176:179], v[192:195], v[52:55]
	v_mfma_f32_16x16x32_bf16 v[52:55], v[180:183], v[196:199], v[52:55]
	v_mfma_f32_16x16x32_bf16 v[36:39], v[176:179], v[200:203], v[36:39]
	v_mfma_f32_16x16x32_bf16 v[36:39], v[180:183], v[204:207], v[36:39]
	v_mfma_f32_16x16x32_bf16 v[20:23], v[176:179], v[208:211], v[20:23]
	v_mfma_f32_16x16x32_bf16 v[20:23], v[180:183], v[212:215], v[20:23]
	v_mfma_f32_16x16x32_bf16 v[4:7], v[176:179], v[216:219], v[4:7]
	v_mfma_f32_16x16x32_bf16 v[4:7], v[180:183], v[220:223], v[4:7]
	v_mfma_f32_16x16x32_bf16 v[0:3], v[184:187], v[216:219], v[0:3]
	v_mfma_f32_16x16x32_bf16 v[0:3], v[188:191], v[220:223], v[0:3]
	v_mfma_f32_16x16x32_bf16 v[16:19], v[184:187], v[208:211], v[16:19]
	v_mfma_f32_16x16x32_bf16 v[16:19], v[188:191], v[212:215], v[16:19]
	v_mfma_f32_16x16x32_bf16 v[32:35], v[184:187], v[200:203], v[32:35]
	v_mfma_f32_16x16x32_bf16 v[32:35], v[188:191], v[204:207], v[32:35]
	s_setprio 2
	s_barrier
	v_mfma_f32_16x16x32_bf16 v[48:51], v[184:187], v[192:195], v[48:51]
	v_mfma_f32_16x16x32_bf16 v[48:51], v[188:191], v[196:199], v[48:51]
	s_setprio 0
	s_add_i32 s90, s90, 2
	s_add_u32 s74, s74, 0x100
	s_addc_u32 s75, s75, 0
	s_add_u32 s88, s88, 0x100
	s_addc_u32 s89, s89, 0
	s_cmp_gt_u32 s90, 29
	s_cbranch_scc0 .LBB0_102
	s_and_b64 vcc, exec, s[22:23]
	s_cbranch_vccz .LBB0_105
	s_barrier

; #define PG8_STAGE(bufoff, gbase, voff) do { _Pragma("unroll") for (int _i = 0; _i < 2; ++_i) \
;         __builtin_amdgcn_global_load_lds((const unsigned*)((const char*)(gbase) + (voff)[_i]), (PG8_LAS unsigned*)(lds + (bufoff) + ldsw + _i * 8192), 16, 0, 0); } while (0)
; #define PG8_LDA(dst, b, h) do { _Pragma("unroll") for (int m = 0; m < 4; ++m) _Pragma("unroll") for (int k = 0; k < 2; ++k) dst[m][k] = *(const PG8_LAS bf16x8*)(lds + PG8_SA(b, h) + aoff + m * 2048 + k * 1024); } while (0)
; #define PG8_LDB(dst, b, h) do { _Pragma("unroll") for (int n = 0; n < 2; ++n) _Pragma("unroll") for (int k = 0; k < 2; ++k) dst[n][k] = *(const PG8_LAS bf16x8*)(lds + PG8_SB(b, h) + boff + n * 2048 + k * 1024); } while (0)
; #define PG8_MMA(ai, bj, At, Bt) do { __builtin_amdgcn_s_setprio(1); _Pragma("unroll") for (int m = 0; m < 4; ++m) _Pragma("unroll") for (int n = 0; n < 2; ++n) _Pragma("unroll") for (int k = 0; k < 2; ++k) \
;         acc[ai][bj][m][n] = __builtin_amdgcn_mfma_f32_16x16x32_bf16(Bt[n][k], At[m][k], acc[ai][bj][m][n], 0, 0, 0); __builtin_amdgcn_s_setprio(0); } while (0)
; #define PG8_WAIT_V(n) asm volatile("s_waitcnt vmcnt(" #n ")" ::: "memory")
; #define PG8_BAR __builtin_amdgcn_s_barrier()
; template <class Epi, class Sched, bool ALIGN_EPI = false, bool SP2 = false>
; __device__ __forceinline__ void gemm_phase(PG8_LAS unsigned char* lds, const Gemm g, const Sched& S, const Epi& E) {
;     ...
;         for (int t = 0; t < nt; t += 2) {
;             const bool last = (t == nt - 2);
;             const char* a1 = cA + (size_t)(t + 1) * kstep;
;             const char* a2 = last ? nA : cA + (size_t)(t + 2) * kstep; const char* b2 = last ? nB : cB + (size_t)(t + 2) * kstep;
;             const char* a3 = a2 + kstep; const char* b3 = b2 + kstep;
;             if (last && has_next) S.a_ready(nxt);
;             if constexpr (SP2) {
;             PG8_LDB(B0, 0, 0); PG8_LDB(B1, 0, 1); PG8_SCHED; PG8_LDA(At, 0, 0); PG8_STAGE(PG8_SA(1, 1), a1 + hstep, voffA);
;             PG8_WAIT_V(8); PG8_WAIT_L(0); PG8_BAR; PG8_MMA(0, 0, At, B0); PG8_MMA(0, 1, At, B1); PG8_BAR; PG8_SCHED;
;             PG8_LDA(At, 0, 1); PG8_STAGE(PG8_SB(0, 0), b2, voffB); PG8_STAGE(PG8_SB(0, 1), b2 + hstep, voffB); PG8_STAGE(PG8_SA(0, 0), a2, voffA);
;             PG8_WAIT_V(8); PG8_WAIT_L(0); PG8_BAR; PG8_MMA(1, 0, At, B0); PG8_MMA(1, 1, At, B1); PG8_BAR; PG8_SCHED;
.LBB0_179:
	ds_read_b128 v[144:147], v155
	ds_read_b128 v[160:163], v155 offset:1024
	ds_read_b128 v[164:167], v155 offset:2048
	ds_read_b128 v[168:171], v155 offset:3072
	ds_read_b128 v[172:175], v156
	ds_read_b128 v[176:179], v156 offset:1024
	ds_read_b128 v[180:183], v156 offset:2048
	ds_read_b128 v[184:187], v156 offset:3072
	s_add_u32 s62, s76, 0xffea0080
	s_addc_u32 s63, s77, -1
	s_cmpk_eq_i32 s92, 0x54
	s_cselect_b32 s81, s7, s63
	s_cselect_b32 s80, s6, s62
	s_cselect_b32 s79, s75, s91
	s_cselect_b32 s78, s74, s50
	v_lshl_add_u64 v[220:221], s[76:77], 0, v[136:137]
	s_add_i32 m0, s52, 0xc000
	ds_read_b128 v[188:191], v157
	ds_read_b128 v[192:195], v157 offset:1024
	ds_read_b128 v[196:199], v157 offset:2048
	ds_read_b128 v[200:203], v157 offset:3072
	ds_read_b128 v[204:207], v157 offset:4096
	ds_read_b128 v[208:211], v157 offset:5120
	ds_read_b128 v[212:215], v157 offset:6144
	ds_read_b128 v[216:219], v157 offset:7168
	global_load_lds_dwordx4 v[220:221], off
	v_lshl_add_u64 v[220:221], s[76:77], 0, v[138:139]
	s_add_i32 m0, s52, 0xe000
	s_nop 0
	global_load_lds_dwordx4 v[220:221], off
	s_waitcnt vmcnt(8)
	s_waitcnt lgkmcnt(0)
	s_setprio 1
	s_barrier
	v_mfma_f32_16x16x32_bf16 v[124:127], v[144:147], v[188:191], v[124:127]
	v_mfma_f32_16x16x32_bf16 v[124:127], v[160:163], v[192:195], v[124:127]
	v_mfma_f32_16x16x32_bf16 v[108:111], v[144:147], v[196:199], v[108:111]
	v_mfma_f32_16x16x32_bf16 v[108:111], v[160:163], v[200:203], v[108:111]
	v_mfma_f32_16x16x32_bf16 v[92:95], v[144:147], v[204:207], v[92:95]
	v_mfma_f32_16x16x32_bf16 v[92:95], v[160:163], v[208:211], v[92:95]
	v_mfma_f32_16x16x32_bf16 v[76:79], v[144:147], v[212:215], v[76:79]
	v_mfma_f32_16x16x32_bf16 v[76:79], v[160:163], v[216:219], v[76:79]
	v_mfma_f32_16x16x32_bf16 v[72:75], v[164:167], v[212:215], v[72:75]
	v_mfma_f32_16x16x32_bf16 v[72:75], v[168:171], v[216:219], v[72:75]
	v_mfma_f32_16x16x32_bf16 v[88:91], v[164:167], v[204:207], v[88:91]
	v_mfma_f32_16x16x32_bf16 v[88:91], v[168:171], v[208:211], v[88:91]
	v_mfma_f32_16x16x32_bf16 v[104:107], v[164:167], v[196:199], v[104:107]
	v_mfma_f32_16x16x32_bf16 v[104:107], v[168:171], v[200:203], v[104:107]
	v_mfma_f32_16x16x32_bf16 v[120:123], v[164:167], v[188:191], v[120:123]
	v_mfma_f32_16x16x32_bf16 v[120:123], v[168:171], v[192:195], v[120:123]
	v_mfma_f32_16x16x32_bf16 v[116:119], v[172:175], v[188:191], v[116:119]
	v_mfma_f32_16x16x32_bf16 v[116:119], v[176:179], v[192:195], v[116:119]
	v_mfma_f32_16x16x32_bf16 v[100:103], v[172:175], v[196:199], v[100:103]
	v_mfma_f32_16x16x32_bf16 v[100:103], v[176:179], v[200:203], v[100:103]
	v_mfma_f32_16x16x32_bf16 v[84:87], v[172:175], v[204:207], v[84:87]
	v_mfma_f32_16x16x32_bf16 v[84:87], v[176:179], v[208:211], v[84:87]
	v_mfma_f32_16x16x32_bf16 v[68:71], v[172:175], v[212:215], v[68:71]
	v_mfma_f32_16x16x32_bf16 v[68:71], v[176:179], v[216:219], v[68:71]
	v_mfma_f32_16x16x32_bf16 v[64:67], v[180:183], v[212:215], v[64:67]
	v_mfma_f32_16x16x32_bf16 v[64:67], v[184:187], v[216:219], v[64:67]
	v_mfma_f32_16x16x32_bf16 v[80:83], v[180:183], v[204:207], v[80:83]
	v_mfma_f32_16x16x32_bf16 v[80:83], v[184:187], v[208:211], v[80:83]
	v_mfma_f32_16x16x32_bf16 v[96:99], v[180:183], v[196:199], v[96:99]
	v_mfma_f32_16x16x32_bf16 v[96:99], v[184:187], v[200:203], v[96:99]
	s_setprio 2
	s_barrier
	v_mfma_f32_16x16x32_bf16 v[112:115], v[180:183], v[188:191], v[112:115]
	v_mfma_f32_16x16x32_bf16 v[112:115], v[184:187], v[192:195], v[112:115]
	s_setprio 0
	s_add_i32 s62, s86, s35
	v_lshl_add_u64 v[220:221], s[78:79], 0, v[130:131]
	s_mov_b32 m0, s62
	ds_read_b128 v[188:191], v157 offset:16384
	ds_read_b128 v[192:195], v157 offset:17408
	ds_read_b128 v[196:199], v157 offset:18432
	ds_read_b128 v[200:203], v157 offset:19456
	ds_read_b128 v[204:207], v157 offset:20480
	ds_read_b128 v[208:211], v157 offset:21504
	ds_read_b128 v[212:215], v157 offset:22528
	ds_read_b128 v[216:219], v157 offset:23552
	global_load_lds_dwordx4 v[220:221], off
	s_add_i32 m0, s62, 0x2000
	s_add_u32 s94, s78, 0x160000
	v_lshl_add_u64 v[222:223], s[78:79], 0, v[134:135]
	s_addc_u32 s95, s79, 0
	s_add_i32 s62, s87, s35
	global_load_lds_dwordx4 v[222:223], off
	v_lshl_add_u64 v[224:225], s[94:95], 0, v[130:131]
	s_mov_b32 m0, s62
	v_lshl_add_u64 v[226:227], s[80:81], 0, v[132:133]
	global_load_lds_dwordx4 v[224:225], off
	v_lshl_add_u64 v[224:225], s[94:95], 0, v[134:135]
	s_add_i32 m0, s62, 0x2000
	s_nop 0
	global_load_lds_dwordx4 v[224:225], off
	v_lshl_add_u64 v[224:225], s[80:81], 0, v[128:129]
	s_mov_b32 m0, s52
	s_nop 0
	global_load_lds_dwordx4 v[224:225], off
	s_mov_b32 m0, s53
	s_nop 0
	global_load_lds_dwordx4 v[226:227], off
	s_waitcnt vmcnt(8)
	s_waitcnt lgkmcnt(0)
	s_setprio 1
	s_barrier
; #define PG8_STAGE(bufoff, gbase, voff) do { _Pragma("unroll") for (int _i = 0; _i < 2; ++_i) \
;         __builtin_amdgcn_global_load_lds((const unsigned*)((const char*)(gbase) + (voff)[_i]), (PG8_LAS unsigned*)(lds + (bufoff) + ldsw + _i * 8192), 16, 0, 0); } while (0)
; #define PG8_LDA(dst, b, h) do { _Pragma("unroll") for (int m = 0; m < 4; ++m) _Pragma("unroll") for (int k = 0; k < 2; ++k) dst[m][k] = *(const PG8_LAS bf16x8*)(lds + PG8_SA(b, h) + aoff + m * 2048 + k * 1024); } while (0)
; #define PG8_LDB(dst, b, h) do { _Pragma("unroll") for (int n = 0; n < 2; ++n) _Pragma("unroll") for (int k = 0; k < 2; ++k) dst[n][k] = *(const PG8_LAS bf16x8*)(lds + PG8_SB(b, h) + boff + n * 2048 + k * 1024); } while (0)
; #define PG8_MMA(ai, bj, At, Bt) do { __builtin_amdgcn_s_setprio(1); _Pragma("unroll") for (int m = 0; m < 4; ++m) _Pragma("unroll") for (int n = 0; n < 2; ++n) _Pragma("unroll") for (int k = 0; k < 2; ++k) \
;         acc[ai][bj][m][n] = __builtin_amdgcn_mfma_f32_16x16x32_bf16(Bt[n][k], At[m][k], acc[ai][bj][m][n], 0, 0, 0); __builtin_amdgcn_s_setprio(0); } while (0)
; #define PG8_WAIT_V(n) asm volatile("s_waitcnt vmcnt(" #n ")" ::: "memory")
; #define PG8_WAIT_L(n) asm volatile("s_waitcnt lgkmcnt(" #n ")" ::: "memory")
; #define PG8_BAR __builtin_amdgcn_s_barrier()
; #define PG8_SCHED __builtin_amdgcn_sched_barrier(0)
; template <class Epi, class Sched, bool ALIGN_EPI = false, bool SP2 = false>
; __device__ __forceinline__ void gemm_phase(PG8_LAS unsigned char* lds, const Gemm g, const Sched& S, const Epi& E) {
;     ...
;             PG8_WAIT_V(8); PG8_WAIT_L(0); PG8_BAR; PG8_MMA(1, 0, At, B0); PG8_MMA(1, 1, At, B1); PG8_BAR; PG8_SCHED;
;             PG8_LDB(B0, 1, 0); PG8_LDB(B1, 1, 1); PG8_SCHED; PG8_LDA(At, 1, 0); PG8_STAGE(PG8_SA(0, 1), a2 + hstep, voffA);
;             PG8_WAIT_V(8); PG8_WAIT_L(0); PG8_BAR; PG8_MMA(0, 0, At, B0); PG8_MMA(0, 1, At, B1); PG8_BAR; PG8_SCHED;
	v_mfma_f32_16x16x32_bf16 v[60:63], v[144:147], v[188:191], v[60:63]
	v_mfma_f32_16x16x32_bf16 v[60:63], v[160:163], v[192:195], v[60:63]
	v_mfma_f32_16x16x32_bf16 v[44:47], v[144:147], v[196:199], v[44:47]
	v_mfma_f32_16x16x32_bf16 v[44:47], v[160:163], v[200:203], v[44:47]
	v_mfma_f32_16x16x32_bf16 v[28:31], v[144:147], v[204:207], v[28:31]
	v_mfma_f32_16x16x32_bf16 v[28:31], v[160:163], v[208:211], v[28:31]
	v_mfma_f32_16x16x32_bf16 v[12:15], v[144:147], v[212:215], v[12:15]
	v_mfma_f32_16x16x32_bf16 v[12:15], v[160:163], v[216:219], v[12:15]
	v_mfma_f32_16x16x32_bf16 v[8:11], v[164:167], v[212:215], v[8:11]
	v_mfma_f32_16x16x32_bf16 v[8:11], v[168:171], v[216:219], v[8:11]
	v_mfma_f32_16x16x32_bf16 v[24:27], v[164:167], v[204:207], v[24:27]
	v_mfma_f32_16x16x32_bf16 v[24:27], v[168:171], v[208:211], v[24:27]
	v_mfma_f32_16x16x32_bf16 v[40:43], v[164:167], v[196:199], v[40:43]
	v_mfma_f32_16x16x32_bf16 v[40:43], v[168:171], v[200:203], v[40:43]
	v_mfma_f32_16x16x32_bf16 v[56:59], v[164:167], v[188:191], v[56:59]
	v_mfma_f32_16x16x32_bf16 v[56:59], v[168:171], v[192:195], v[56:59]
	v_mfma_f32_16x16x32_bf16 v[52:55], v[172:175], v[188:191], v[52:55]
	v_mfma_f32_16x16x32_bf16 v[52:55], v[176:179], v[192:195], v[52:55]
	v_mfma_f32_16x16x32_bf16 v[36:39], v[172:175], v[196:199], v[36:39]
	v_mfma_f32_16x16x32_bf16 v[36:39], v[176:179], v[200:203], v[36:39]
	v_mfma_f32_16x16x32_bf16 v[20:23], v[172:175], v[204:207], v[20:23]
	v_mfma_f32_16x16x32_bf16 v[20:23], v[176:179], v[208:211], v[20:23]
	v_mfma_f32_16x16x32_bf16 v[4:7], v[172:175], v[212:215], v[4:7]
	v_mfma_f32_16x16x32_bf16 v[4:7], v[176:179], v[216:219], v[4:7]
	v_mfma_f32_16x16x32_bf16 v[0:3], v[180:183], v[212:215], v[0:3]
	v_mfma_f32_16x16x32_bf16 v[0:3], v[184:187], v[216:219], v[0:3]
	v_mfma_f32_16x16x32_bf16 v[16:19], v[180:183], v[204:207], v[16:19]
	v_mfma_f32_16x16x32_bf16 v[16:19], v[184:187], v[208:211], v[16:19]
	v_mfma_f32_16x16x32_bf16 v[32:35], v[180:183], v[196:199], v[32:35]
	v_mfma_f32_16x16x32_bf16 v[32:35], v[184:187], v[200:203], v[32:35]
	s_setprio 2
	s_barrier
	v_mfma_f32_16x16x32_bf16 v[48:51], v[180:183], v[188:191], v[48:51]
	v_mfma_f32_16x16x32_bf16 v[48:51], v[184:187], v[192:195], v[48:51]
	s_setprio 0
	s_add_i32 s62, 0, 0x18000
	v_add_u32_e32 v159, s62, v153
	s_add_i32 s63, 0, 0x1c000
	ds_read_b128 v[144:147], v159
	ds_read_b128 v[160:163], v159 offset:1024
	ds_read_b128 v[164:167], v159 offset:2048
	ds_read_b128 v[168:171], v159 offset:3072
	v_add_u32_e32 v159, s63, v153
	ds_read_b128 v[172:175], v159
	ds_read_b128 v[176:179], v159 offset:1024
	ds_read_b128 v[180:183], v159 offset:2048
	ds_read_b128 v[184:187], v159 offset:3072
	s_add_u32 s80, s80, 0x160000
	s_addc_u32 s81, s81, 0
	s_mov_b32 m0, s61
	v_lshl_add_u64 v[228:229], s[80:81], 0, v[128:129]
	ds_read_b128 v[188:191], v157 offset:32768
	ds_read_b128 v[192:195], v157 offset:33792
	ds_read_b128 v[196:199], v157 offset:34816
	ds_read_b128 v[200:203], v157 offset:35840
	ds_read_b128 v[204:207], v157 offset:36864
	ds_read_b128 v[208:211], v157 offset:37888
	ds_read_b128 v[212:215], v157 offset:38912
	ds_read_b128 v[216:219], v157 offset:39936
	global_load_lds_dwordx4 v[228:229], off
	v_lshl_add_u64 v[228:229], s[80:81], 0, v[132:133]
	s_mov_b32 m0, s65
	s_nop 0
	global_load_lds_dwordx4 v[228:229], off
	s_waitcnt vmcnt(8)
	s_waitcnt lgkmcnt(0)
	s_setprio 1
	s_barrier
	v_mfma_f32_16x16x32_bf16 v[124:127], v[144:147], v[188:191], v[124:127]
	v_mfma_f32_16x16x32_bf16 v[124:127], v[160:163], v[192:195], v[124:127]
	v_mfma_f32_16x16x32_bf16 v[108:111], v[144:147], v[196:199], v[108:111]
	v_mfma_f32_16x16x32_bf16 v[108:111], v[160:163], v[200:203], v[108:111]
	v_mfma_f32_16x16x32_bf16 v[92:95], v[144:147], v[204:207], v[92:95]
	v_mfma_f32_16x16x32_bf16 v[92:95], v[160:163], v[208:211], v[92:95]
	v_mfma_f32_16x16x32_bf16 v[76:79], v[144:147], v[212:215], v[76:79]
	v_mfma_f32_16x16x32_bf16 v[76:79], v[160:163], v[216:219], v[76:79]
	v_mfma_f32_16x16x32_bf16 v[72:75], v[164:167], v[212:215], v[72:75]
	v_mfma_f32_16x16x32_bf16 v[72:75], v[168:171], v[216:219], v[72:75]
	v_mfma_f32_16x16x32_bf16 v[88:91], v[164:167], v[204:207], v[88:91]
	v_mfma_f32_16x16x32_bf16 v[88:91], v[168:171], v[208:211], v[88:91]
	v_mfma_f32_16x16x32_bf16 v[104:107], v[164:167], v[196:199], v[104:107]
	v_mfma_f32_16x16x32_bf16 v[104:107], v[168:171], v[200:203], v[104:107]
	v_mfma_f32_16x16x32_bf16 v[120:123], v[164:167], v[188:191], v[120:123]
	v_mfma_f32_16x16x32_bf16 v[120:123], v[168:171], v[192:195], v[120:123]
	v_mfma_f32_16x16x32_bf16 v[116:119], v[172:175], v[188:191], v[116:119]
	v_mfma_f32_16x16x32_bf16 v[116:119], v[176:179], v[192:195], v[116:119]
	v_mfma_f32_16x16x32_bf16 v[100:103], v[172:175], v[196:199], v[100:103]
	v_mfma_f32_16x16x32_bf16 v[100:103], v[176:179], v[200:203], v[100:103]
	v_mfma_f32_16x16x32_bf16 v[84:87], v[172:175], v[204:207], v[84:87]
	v_mfma_f32_16x16x32_bf16 v[84:87], v[176:179], v[208:211], v[84:87]
	v_mfma_f32_16x16x32_bf16 v[68:71], v[172:175], v[212:215], v[68:71]
	v_mfma_f32_16x16x32_bf16 v[68:71], v[176:179], v[216:219], v[68:71]
	v_mfma_f32_16x16x32_bf16 v[64:67], v[180:183], v[212:215], v[64:67]
	v_mfma_f32_16x16x32_bf16 v[64:67], v[184:187], v[216:219], v[64:67]
	v_mfma_f32_16x16x32_bf16 v[80:83], v[180:183], v[204:207], v[80:83]
	v_mfma_f32_16x16x32_bf16 v[80:83], v[184:187], v[208:211], v[80:83]
	v_mfma_f32_16x16x32_bf16 v[96:99], v[180:183], v[196:199], v[96:99]
	v_mfma_f32_16x16x32_bf16 v[96:99], v[184:187], v[200:203], v[96:99]
	s_setprio 2
	s_barrier
; #define PG8_STAGE(bufoff, gbase, voff) do { _Pragma("unroll") for (int _i = 0; _i < 2; ++_i) \
;         __builtin_amdgcn_global_load_lds((const unsigned*)((const char*)(gbase) + (voff)[_i]), (PG8_LAS unsigned*)(lds + (bufoff) + ldsw + _i * 8192), 16, 0, 0); } while (0)
; #define PG8_LDA(dst, b, h) do { _Pragma("unroll") for (int m = 0; m < 4; ++m) _Pragma("unroll") for (int k = 0; k < 2; ++k) dst[m][k] = *(const PG8_LAS bf16x8*)(lds + PG8_SA(b, h) + aoff + m * 2048 + k * 1024); } while (0)
; #define PG8_MMA(ai, bj, At, Bt) do { __builtin_amdgcn_s_setprio(1); _Pragma("unroll") for (int m = 0; m < 4; ++m) _Pragma("unroll") for (int n = 0; n < 2; ++n) _Pragma("unroll") for (int k = 0; k < 2; ++k) \
;         acc[ai][bj][m][n] = __builtin_amdgcn_mfma_f32_16x16x32_bf16(Bt[n][k], At[m][k], acc[ai][bj][m][n], 0, 0, 0); __builtin_amdgcn_s_setprio(0); } while (0)
; #define PG8_WAIT_V(n) asm volatile("s_waitcnt vmcnt(" #n ")" ::: "memory")
; #define PG8_WAIT_L(n) asm volatile("s_waitcnt lgkmcnt(" #n ")" ::: "memory")
; #define PG8_BAR __builtin_amdgcn_s_barrier()
; #define PG8_SCHED __builtin_amdgcn_sched_barrier(0)
; template <class Epi, class Sched, bool ALIGN_EPI = false, bool SP2 = false>
; __device__ __forceinline__ void gemm_phase(PG8_LAS unsigned char* lds, const Gemm g, const Sched& S, const Epi& E) {
;     ...
;         for (int t = 0; t < nt; t += 2) {
;     ...
;             PG8_WAIT_V(8); PG8_WAIT_L(0); PG8_BAR; PG8_MMA(0, 0, At, B0); PG8_MMA(0, 1, At, B1); PG8_BAR; PG8_SCHED;
;             PG8_LDA(At, 1, 1); PG8_STAGE(PG8_SB(1, 0), b3, voffB); PG8_STAGE(PG8_SB(1, 1), b3 + hstep, voffB); PG8_STAGE(PG8_SA(1, 0), a3, voffA);
;             PG8_WAIT_V(8); PG8_WAIT_L(0); PG8_BAR; PG8_MMA(1, 0, At, B0); PG8_MMA(1, 1, At, B1); PG8_BAR; PG8_SCHED;
	v_mfma_f32_16x16x32_bf16 v[112:115], v[180:183], v[188:191], v[112:115]
	v_mfma_f32_16x16x32_bf16 v[112:115], v[184:187], v[192:195], v[112:115]
	s_setprio 0
	s_add_i32 s62, s62, s35
	v_lshl_add_u64 v[220:221], v[220:221], 0, s[56:57]
	s_mov_b32 m0, s62
	ds_read_b128 v[188:191], v157 offset:49152
	ds_read_b128 v[192:195], v157 offset:50176
	ds_read_b128 v[196:199], v157 offset:51200
	ds_read_b128 v[200:203], v157 offset:52224
	ds_read_b128 v[204:207], v157 offset:53248
	ds_read_b128 v[208:211], v157 offset:54272
	ds_read_b128 v[212:215], v157 offset:55296
	ds_read_b128 v[216:219], v157 offset:56320
	global_load_lds_dwordx4 v[220:221], off
	s_add_i32 m0, s62, 0x2000
	s_add_u32 s78, s78, 0x160080
	v_lshl_add_u64 v[220:221], v[222:223], 0, s[56:57]
	s_addc_u32 s79, s79, 0
	s_add_i32 s62, s63, s35
	global_load_lds_dwordx4 v[220:221], off
	v_lshl_add_u64 v[220:221], s[78:79], 0, v[130:131]
	s_mov_b32 m0, s62
	s_nop 0
	global_load_lds_dwordx4 v[220:221], off
	v_lshl_add_u64 v[220:221], s[78:79], 0, v[134:135]
	s_add_i32 m0, s62, 0x2000
	s_nop 0
	global_load_lds_dwordx4 v[220:221], off
	v_lshl_add_u64 v[220:221], v[224:225], 0, s[56:57]
	s_mov_b32 m0, s83
	s_nop 0
	global_load_lds_dwordx4 v[220:221], off
	v_lshl_add_u64 v[220:221], v[226:227], 0, s[56:57]
	s_mov_b32 m0, s84
	s_nop 0
	global_load_lds_dwordx4 v[220:221], off
	s_waitcnt vmcnt(8)
	s_waitcnt lgkmcnt(0)
	s_setprio 1
	s_barrier
	v_mfma_f32_16x16x32_bf16 v[60:63], v[144:147], v[188:191], v[60:63]
	v_mfma_f32_16x16x32_bf16 v[60:63], v[160:163], v[192:195], v[60:63]
	v_mfma_f32_16x16x32_bf16 v[44:47], v[144:147], v[196:199], v[44:47]
	v_mfma_f32_16x16x32_bf16 v[44:47], v[160:163], v[200:203], v[44:47]
	v_mfma_f32_16x16x32_bf16 v[28:31], v[144:147], v[204:207], v[28:31]
	v_mfma_f32_16x16x32_bf16 v[28:31], v[160:163], v[208:211], v[28:31]
	v_mfma_f32_16x16x32_bf16 v[12:15], v[144:147], v[212:215], v[12:15]
	v_mfma_f32_16x16x32_bf16 v[12:15], v[160:163], v[216:219], v[12:15]
	v_mfma_f32_16x16x32_bf16 v[8:11], v[164:167], v[212:215], v[8:11]
	v_mfma_f32_16x16x32_bf16 v[8:11], v[168:171], v[216:219], v[8:11]
	v_mfma_f32_16x16x32_bf16 v[24:27], v[164:167], v[204:207], v[24:27]
	v_mfma_f32_16x16x32_bf16 v[24:27], v[168:171], v[208:211], v[24:27]
	v_mfma_f32_16x16x32_bf16 v[40:43], v[164:167], v[196:199], v[40:43]
	v_mfma_f32_16x16x32_bf16 v[40:43], v[168:171], v[200:203], v[40:43]
	v_mfma_f32_16x16x32_bf16 v[56:59], v[164:167], v[188:191], v[56:59]
	v_mfma_f32_16x16x32_bf16 v[56:59], v[168:171], v[192:195], v[56:59]
	v_mfma_f32_16x16x32_bf16 v[52:55], v[172:175], v[188:191], v[52:55]
	v_mfma_f32_16x16x32_bf16 v[52:55], v[176:179], v[192:195], v[52:55]
	v_mfma_f32_16x16x32_bf16 v[36:39], v[172:175], v[196:199], v[36:39]
	v_mfma_f32_16x16x32_bf16 v[36:39], v[176:179], v[200:203], v[36:39]
	v_mfma_f32_16x16x32_bf16 v[20:23], v[172:175], v[204:207], v[20:23]
	v_mfma_f32_16x16x32_bf16 v[20:23], v[176:179], v[208:211], v[20:23]
	v_mfma_f32_16x16x32_bf16 v[4:7], v[172:175], v[212:215], v[4:7]
	v_mfma_f32_16x16x32_bf16 v[4:7], v[176:179], v[216:219], v[4:7]
	v_mfma_f32_16x16x32_bf16 v[0:3], v[180:183], v[212:215], v[0:3]
	v_mfma_f32_16x16x32_bf16 v[0:3], v[184:187], v[216:219], v[0:3]
	v_mfma_f32_16x16x32_bf16 v[16:19], v[180:183], v[204:207], v[16:19]
	v_mfma_f32_16x16x32_bf16 v[16:19], v[184:187], v[208:211], v[16:19]
	v_mfma_f32_16x16x32_bf16 v[32:35], v[180:183], v[196:199], v[32:35]
	v_mfma_f32_16x16x32_bf16 v[32:35], v[184:187], v[200:203], v[32:35]
	s_setprio 2
	s_barrier
	v_mfma_f32_16x16x32_bf16 v[48:51], v[180:183], v[188:191], v[48:51]
	v_mfma_f32_16x16x32_bf16 v[48:51], v[184:187], v[192:195], v[48:51]
	s_setprio 0
	s_add_i32 s92, s92, 2
	s_add_u32 s76, s76, 0x100
	s_addc_u32 s77, s77, 0
	s_add_u32 s50, s50, 0x100
	s_addc_u32 s91, s91, 0
	s_cmpk_gt_u32 s92, 0x55
	s_cbranch_scc0 .LBB0_179
	s_and_b64 vcc, exec, s[58:59]
	s_cbranch_vccz .LBB0_182
	s_barrier

; #define PG8_STAGE(bufoff, gbase, voff) do { _Pragma("unroll") for (int _i = 0; _i < 2; ++_i) \
;         __builtin_amdgcn_global_load_lds((const unsigned*)((const char*)(gbase) + (voff)[_i]), (PG8_LAS unsigned*)(lds + (bufoff) + ldsw + _i * 8192), 16, 0, 0); } while (0)
; #define PG8_LDA(dst, b, h) do { _Pragma("unroll") for (int m = 0; m < 4; ++m) _Pragma("unroll") for (int k = 0; k < 2; ++k) dst[m][k] = *(const PG8_LAS bf16x8*)(lds + PG8_SA(b, h) + aoff + m * 2048 + k * 1024); } while (0)
; #define PG8_LDB(dst, b, h) do { _Pragma("unroll") for (int n = 0; n < 2; ++n) _Pragma("unroll") for (int k = 0; k < 2; ++k) dst[n][k] = *(const PG8_LAS bf16x8*)(lds + PG8_SB(b, h) + boff + n * 2048 + k * 1024); } while (0)
; #define PG8_MMA(ai, bj, At, Bt) do { __builtin_amdgcn_s_setprio(1); _Pragma("unroll") for (int m = 0; m < 4; ++m) _Pragma("unroll") for (int n = 0; n < 2; ++n) _Pragma("unroll") for (int k = 0; k < 2; ++k) \
;         acc[ai][bj][m][n] = __builtin_amdgcn_mfma_f32_16x16x32_bf16(Bt[n][k], At[m][k], acc[ai][bj][m][n], 0, 0, 0); __builtin_amdgcn_s_setprio(0); } while (0)
; #define PG8_WAIT_V(n) asm volatile("s_waitcnt vmcnt(" #n ")" ::: "memory")
; #define PG8_BAR __builtin_amdgcn_s_barrier()
; template <class Epi, class Sched, bool ALIGN_EPI = false, bool SP2 = false>
; __device__ __forceinline__ void gemm_phase(PG8_LAS unsigned char* lds, const Gemm g, const Sched& S, const Epi& E) {
;     ...
;         for (int t = 0; t < nt; t += 2) {
;             const bool last = (t == nt - 2);
;             const char* a1 = cA + (size_t)(t + 1) * kstep;
;             const char* a2 = last ? nA : cA + (size_t)(t + 2) * kstep; const char* b2 = last ? nB : cB + (size_t)(t + 2) * kstep;
;             const char* a3 = a2 + kstep; const char* b3 = b2 + kstep;
;             if (last && has_next) S.a_ready(nxt);
;             if constexpr (SP2) {
;             PG8_LDB(B0, 0, 0); PG8_LDB(B1, 0, 1); PG8_SCHED; PG8_LDA(At, 0, 0); PG8_STAGE(PG8_SA(1, 1), a1 + hstep, voffA);
;             PG8_WAIT_V(8); PG8_WAIT_L(0); PG8_BAR; PG8_MMA(0, 0, At, B0); PG8_MMA(0, 1, At, B1); PG8_BAR; PG8_SCHED;
;             PG8_LDA(At, 0, 1); PG8_STAGE(PG8_SB(0, 0), b2, voffB); PG8_STAGE(PG8_SB(0, 1), b2 + hstep, voffB); PG8_STAGE(PG8_SA(0, 0), a2, voffA);
;             PG8_WAIT_V(8); PG8_WAIT_L(0); PG8_BAR; PG8_MMA(1, 0, At, B0); PG8_MMA(1, 1, At, B1); PG8_BAR; PG8_SCHED;
.LBB0_326:
	ds_read_b128 v[178:181], v176
	ds_read_b128 v[182:185], v176 offset:1024
	ds_read_b128 v[186:189], v176 offset:2048
	ds_read_b128 v[190:193], v176 offset:3072
	ds_read_b128 v[194:197], v177
	ds_read_b128 v[198:201], v177 offset:1024
	ds_read_b128 v[202:205], v177 offset:2048
	ds_read_b128 v[206:209], v177 offset:3072
	s_add_u32 s62, s76, 0xfff80080
	s_addc_u32 s63, s77, -1
	s_cmp_eq_u32 s75, 28
	s_cselect_b32 s81, s10, s63
	s_cselect_b32 s80, s11, s62
	s_cselect_b32 s79, s51, s67
	s_cselect_b32 s78, s55, s57
	v_lshl_add_u64 v[166:167], s[76:77], 0, v[146:147]
	s_add_i32 m0, s64, 0xc000
	ds_read_b128 v[210:213], v145
	ds_read_b128 v[214:217], v145 offset:1024
	ds_read_b128 v[218:221], v145 offset:2048
	ds_read_b128 v[222:225], v145 offset:3072
	ds_read_b128 v[226:229], v145 offset:4096
	ds_read_b128 v[230:233], v145 offset:5120
	ds_read_b128 v[234:237], v145 offset:6144
	ds_read_b128 v[238:241], v145 offset:7168
	global_load_lds_dwordx4 v[166:167], off
	v_lshl_add_u64 v[166:167], s[76:77], 0, v[152:153]
	s_add_i32 m0, s64, 0xe000
	s_nop 0
	global_load_lds_dwordx4 v[166:167], off
	s_waitcnt vmcnt(8)
	s_waitcnt lgkmcnt(0)
	s_setprio 1
	s_barrier
	v_mfma_f32_16x16x32_bf16 v[124:127], v[178:181], v[210:213], v[124:127]
	v_mfma_f32_16x16x32_bf16 v[124:127], v[182:185], v[214:217], v[124:127]
	v_mfma_f32_16x16x32_bf16 v[116:119], v[178:181], v[218:221], v[116:119]
	v_mfma_f32_16x16x32_bf16 v[116:119], v[182:185], v[222:225], v[116:119]
	v_mfma_f32_16x16x32_bf16 v[108:111], v[178:181], v[226:229], v[108:111]
	v_mfma_f32_16x16x32_bf16 v[108:111], v[182:185], v[230:233], v[108:111]
	v_mfma_f32_16x16x32_bf16 v[100:103], v[178:181], v[234:237], v[100:103]
	v_mfma_f32_16x16x32_bf16 v[100:103], v[182:185], v[238:241], v[100:103]
	v_mfma_f32_16x16x32_bf16 v[96:99], v[186:189], v[234:237], v[96:99]
	v_mfma_f32_16x16x32_bf16 v[96:99], v[190:193], v[238:241], v[96:99]
	v_mfma_f32_16x16x32_bf16 v[104:107], v[186:189], v[226:229], v[104:107]
	v_mfma_f32_16x16x32_bf16 v[104:107], v[190:193], v[230:233], v[104:107]
	v_mfma_f32_16x16x32_bf16 v[112:115], v[186:189], v[218:221], v[112:115]
	v_mfma_f32_16x16x32_bf16 v[112:115], v[190:193], v[222:225], v[112:115]
	v_mfma_f32_16x16x32_bf16 v[120:123], v[186:189], v[210:213], v[120:123]
	v_mfma_f32_16x16x32_bf16 v[120:123], v[190:193], v[214:217], v[120:123]
	v_mfma_f32_16x16x32_bf16 v[68:71], v[194:197], v[210:213], v[68:71]
	v_mfma_f32_16x16x32_bf16 v[68:71], v[198:201], v[214:217], v[68:71]
	v_mfma_f32_16x16x32_bf16 v[52:55], v[194:197], v[218:221], v[52:55]
	v_mfma_f32_16x16x32_bf16 v[52:55], v[198:201], v[222:225], v[52:55]
	v_mfma_f32_16x16x32_bf16 v[44:47], v[194:197], v[226:229], v[44:47]
	v_mfma_f32_16x16x32_bf16 v[44:47], v[198:201], v[230:233], v[44:47]
	v_mfma_f32_16x16x32_bf16 v[36:39], v[194:197], v[234:237], v[36:39]
	v_mfma_f32_16x16x32_bf16 v[36:39], v[198:201], v[238:241], v[36:39]
	v_mfma_f32_16x16x32_bf16 v[32:35], v[202:205], v[234:237], v[32:35]
	v_mfma_f32_16x16x32_bf16 v[32:35], v[206:209], v[238:241], v[32:35]
	v_mfma_f32_16x16x32_bf16 v[40:43], v[202:205], v[226:229], v[40:43]
	v_mfma_f32_16x16x32_bf16 v[40:43], v[206:209], v[230:233], v[40:43]
	v_mfma_f32_16x16x32_bf16 v[48:51], v[202:205], v[218:221], v[48:51]
	v_mfma_f32_16x16x32_bf16 v[48:51], v[206:209], v[222:225], v[48:51]
	s_setprio 2
	s_barrier
	v_mfma_f32_16x16x32_bf16 v[64:67], v[202:205], v[210:213], v[64:67]
	v_mfma_f32_16x16x32_bf16 v[64:67], v[206:209], v[214:217], v[64:67]
	s_setprio 0
	s_add_i32 s62, s53, s3
	v_lshl_add_u64 v[166:167], s[78:79], 0, v[130:131]
	s_mov_b32 m0, s62
	ds_read_b128 v[210:213], v145 offset:16384
	ds_read_b128 v[214:217], v145 offset:17408
	ds_read_b128 v[218:221], v145 offset:18432
	ds_read_b128 v[222:225], v145 offset:19456
	ds_read_b128 v[226:229], v145 offset:20480
	ds_read_b128 v[230:233], v145 offset:21504
	ds_read_b128 v[234:237], v145 offset:22528
	ds_read_b128 v[238:241], v145 offset:23552
	global_load_lds_dwordx4 v[166:167], off
	s_add_i32 m0, s62, 0x2000
	s_add_u32 s82, s78, 0x80000
	v_lshl_add_u64 v[242:243], s[78:79], 0, v[134:135]
	s_addc_u32 s83, s79, 0
	s_add_i32 s62, s66, s3
	global_load_lds_dwordx4 v[242:243], off
	v_lshl_add_u64 v[244:245], s[82:83], 0, v[130:131]
	s_mov_b32 m0, s62
	v_lshl_add_u64 v[246:247], s[80:81], 0, v[132:133]
	global_load_lds_dwordx4 v[244:245], off
	v_lshl_add_u64 v[244:245], s[82:83], 0, v[134:135]
	s_add_i32 m0, s62, 0x2000
	s_nop 0
	global_load_lds_dwordx4 v[244:245], off
	v_lshl_add_u64 v[244:245], s[80:81], 0, v[128:129]
	s_mov_b32 m0, s64
	s_nop 0
	global_load_lds_dwordx4 v[244:245], off
	s_mov_b32 m0, s65
	s_nop 0
	global_load_lds_dwordx4 v[246:247], off
	s_waitcnt vmcnt(8)
	s_waitcnt lgkmcnt(0)
	s_setprio 1
	s_barrier
; #define PG8_STAGE(bufoff, gbase, voff) do { _Pragma("unroll") for (int _i = 0; _i < 2; ++_i) \
;         __builtin_amdgcn_global_load_lds((const unsigned*)((const char*)(gbase) + (voff)[_i]), (PG8_LAS unsigned*)(lds + (bufoff) + ldsw + _i * 8192), 16, 0, 0); } while (0)
; #define PG8_LDA(dst, b, h) do { _Pragma("unroll") for (int m = 0; m < 4; ++m) _Pragma("unroll") for (int k = 0; k < 2; ++k) dst[m][k] = *(const PG8_LAS bf16x8*)(lds + PG8_SA(b, h) + aoff + m * 2048 + k * 1024); } while (0)
; #define PG8_LDB(dst, b, h) do { _Pragma("unroll") for (int n = 0; n < 2; ++n) _Pragma("unroll") for (int k = 0; k < 2; ++k) dst[n][k] = *(const PG8_LAS bf16x8*)(lds + PG8_SB(b, h) + boff + n * 2048 + k * 1024); } while (0)
; #define PG8_MMA(ai, bj, At, Bt) do { __builtin_amdgcn_s_setprio(1); _Pragma("unroll") for (int m = 0; m < 4; ++m) _Pragma("unroll") for (int n = 0; n < 2; ++n) _Pragma("unroll") for (int k = 0; k < 2; ++k) \
;         acc[ai][bj][m][n] = __builtin_amdgcn_mfma_f32_16x16x32_bf16(Bt[n][k], At[m][k], acc[ai][bj][m][n], 0, 0, 0); __builtin_amdgcn_s_setprio(0); } while (0)
; #define PG8_WAIT_V(n) asm volatile("s_waitcnt vmcnt(" #n ")" ::: "memory")
; #define PG8_WAIT_L(n) asm volatile("s_waitcnt lgkmcnt(" #n ")" ::: "memory")
; #define PG8_BAR __builtin_amdgcn_s_barrier()
; #define PG8_SCHED __builtin_amdgcn_sched_barrier(0)
; template <class Epi, class Sched, bool ALIGN_EPI = false, bool SP2 = false>
; __device__ __forceinline__ void gemm_phase(PG8_LAS unsigned char* lds, const Gemm g, const Sched& S, const Epi& E) {
;     ...
;             PG8_WAIT_V(8); PG8_WAIT_L(0); PG8_BAR; PG8_MMA(1, 0, At, B0); PG8_MMA(1, 1, At, B1); PG8_BAR; PG8_SCHED;
;             PG8_LDB(B0, 1, 0); PG8_LDB(B1, 1, 1); PG8_SCHED; PG8_LDA(At, 1, 0); PG8_STAGE(PG8_SA(0, 1), a2 + hstep, voffA);
;             PG8_WAIT_V(8); PG8_WAIT_L(0); PG8_BAR; PG8_MMA(0, 0, At, B0); PG8_MMA(0, 1, At, B1); PG8_BAR; PG8_SCHED;
	v_mfma_f32_16x16x32_bf16 v[92:95], v[178:181], v[210:213], v[92:95]
	v_mfma_f32_16x16x32_bf16 v[92:95], v[182:185], v[214:217], v[92:95]
	v_mfma_f32_16x16x32_bf16 v[84:87], v[178:181], v[218:221], v[84:87]
	v_mfma_f32_16x16x32_bf16 v[84:87], v[182:185], v[222:225], v[84:87]
	v_mfma_f32_16x16x32_bf16 v[76:79], v[178:181], v[226:229], v[76:79]
	v_mfma_f32_16x16x32_bf16 v[76:79], v[182:185], v[230:233], v[76:79]
	v_mfma_f32_16x16x32_bf16 v[60:63], v[178:181], v[234:237], v[60:63]
	v_mfma_f32_16x16x32_bf16 v[60:63], v[182:185], v[238:241], v[60:63]
	v_mfma_f32_16x16x32_bf16 v[56:59], v[186:189], v[234:237], v[56:59]
	v_mfma_f32_16x16x32_bf16 v[56:59], v[190:193], v[238:241], v[56:59]
	v_mfma_f32_16x16x32_bf16 v[72:75], v[186:189], v[226:229], v[72:75]
	v_mfma_f32_16x16x32_bf16 v[72:75], v[190:193], v[230:233], v[72:75]
	v_mfma_f32_16x16x32_bf16 v[80:83], v[186:189], v[218:221], v[80:83]
	v_mfma_f32_16x16x32_bf16 v[80:83], v[190:193], v[222:225], v[80:83]
	v_mfma_f32_16x16x32_bf16 v[88:91], v[186:189], v[210:213], v[88:91]
	v_mfma_f32_16x16x32_bf16 v[88:91], v[190:193], v[214:217], v[88:91]
	v_mfma_f32_16x16x32_bf16 v[28:31], v[194:197], v[210:213], v[28:31]
	v_mfma_f32_16x16x32_bf16 v[28:31], v[198:201], v[214:217], v[28:31]
	v_mfma_f32_16x16x32_bf16 v[20:23], v[194:197], v[218:221], v[20:23]
	v_mfma_f32_16x16x32_bf16 v[20:23], v[198:201], v[222:225], v[20:23]
	v_mfma_f32_16x16x32_bf16 v[12:15], v[194:197], v[226:229], v[12:15]
	v_mfma_f32_16x16x32_bf16 v[12:15], v[198:201], v[230:233], v[12:15]
	v_mfma_f32_16x16x32_bf16 v[4:7], v[194:197], v[234:237], v[4:7]
	v_mfma_f32_16x16x32_bf16 v[4:7], v[198:201], v[238:241], v[4:7]
	v_mfma_f32_16x16x32_bf16 v[0:3], v[202:205], v[234:237], v[0:3]
	v_mfma_f32_16x16x32_bf16 v[0:3], v[206:209], v[238:241], v[0:3]
	v_mfma_f32_16x16x32_bf16 v[8:11], v[202:205], v[226:229], v[8:11]
	v_mfma_f32_16x16x32_bf16 v[8:11], v[206:209], v[230:233], v[8:11]
	v_mfma_f32_16x16x32_bf16 v[16:19], v[202:205], v[218:221], v[16:19]
	v_mfma_f32_16x16x32_bf16 v[16:19], v[206:209], v[222:225], v[16:19]
	s_setprio 2
	s_barrier
	v_mfma_f32_16x16x32_bf16 v[24:27], v[202:205], v[210:213], v[24:27]
	v_mfma_f32_16x16x32_bf16 v[24:27], v[206:209], v[214:217], v[24:27]
	s_setprio 0
	s_add_i32 s62, 0, 0x18000
	s_add_i32 s63, 0, 0x1c000
	v_add_u32_e32 v190, s62, v143
	v_add_u32_e32 v206, s63, v143
	ds_read_b128 v[178:181], v190
	ds_read_b128 v[182:185], v190 offset:1024
	ds_read_b128 v[186:189], v190 offset:2048
	ds_read_b128 v[190:193], v190 offset:3072
	ds_read_b128 v[194:197], v206
	ds_read_b128 v[198:201], v206 offset:1024
	ds_read_b128 v[202:205], v206 offset:2048
	ds_read_b128 v[206:209], v206 offset:3072
	s_add_u32 s80, s80, 0x80000
	s_addc_u32 s81, s81, 0
	s_mov_b32 m0, s86
	v_lshl_add_u64 v[248:249], s[80:81], 0, v[128:129]
	ds_read_b128 v[210:213], v145 offset:32768
	ds_read_b128 v[214:217], v145 offset:33792
	ds_read_b128 v[218:221], v145 offset:34816
	ds_read_b128 v[222:225], v145 offset:35840
	ds_read_b128 v[226:229], v145 offset:36864
	ds_read_b128 v[230:233], v145 offset:37888
	ds_read_b128 v[234:237], v145 offset:38912
	ds_read_b128 v[238:241], v145 offset:39936
	global_load_lds_dwordx4 v[248:249], off
	v_lshl_add_u64 v[248:249], s[80:81], 0, v[132:133]
	s_mov_b32 m0, s87
	s_nop 0
	global_load_lds_dwordx4 v[248:249], off
	s_waitcnt vmcnt(8)
	s_waitcnt lgkmcnt(0)
	s_setprio 1
	s_barrier
	v_mfma_f32_16x16x32_bf16 v[124:127], v[178:181], v[210:213], v[124:127]
	v_mfma_f32_16x16x32_bf16 v[124:127], v[182:185], v[214:217], v[124:127]
	v_mfma_f32_16x16x32_bf16 v[116:119], v[178:181], v[218:221], v[116:119]
	v_mfma_f32_16x16x32_bf16 v[116:119], v[182:185], v[222:225], v[116:119]
	v_mfma_f32_16x16x32_bf16 v[108:111], v[178:181], v[226:229], v[108:111]
	v_mfma_f32_16x16x32_bf16 v[108:111], v[182:185], v[230:233], v[108:111]
	v_mfma_f32_16x16x32_bf16 v[100:103], v[178:181], v[234:237], v[100:103]
	v_mfma_f32_16x16x32_bf16 v[100:103], v[182:185], v[238:241], v[100:103]
	v_mfma_f32_16x16x32_bf16 v[96:99], v[186:189], v[234:237], v[96:99]
	v_mfma_f32_16x16x32_bf16 v[96:99], v[190:193], v[238:241], v[96:99]
	v_mfma_f32_16x16x32_bf16 v[104:107], v[186:189], v[226:229], v[104:107]
	v_mfma_f32_16x16x32_bf16 v[104:107], v[190:193], v[230:233], v[104:107]
	v_mfma_f32_16x16x32_bf16 v[112:115], v[186:189], v[218:221], v[112:115]
	v_mfma_f32_16x16x32_bf16 v[112:115], v[190:193], v[222:225], v[112:115]
	v_mfma_f32_16x16x32_bf16 v[120:123], v[186:189], v[210:213], v[120:123]
	v_mfma_f32_16x16x32_bf16 v[120:123], v[190:193], v[214:217], v[120:123]
	v_mfma_f32_16x16x32_bf16 v[68:71], v[194:197], v[210:213], v[68:71]
	v_mfma_f32_16x16x32_bf16 v[68:71], v[198:201], v[214:217], v[68:71]
	v_mfma_f32_16x16x32_bf16 v[52:55], v[194:197], v[218:221], v[52:55]
	v_mfma_f32_16x16x32_bf16 v[52:55], v[198:201], v[222:225], v[52:55]
	v_mfma_f32_16x16x32_bf16 v[44:47], v[194:197], v[226:229], v[44:47]
	v_mfma_f32_16x16x32_bf16 v[44:47], v[198:201], v[230:233], v[44:47]
	v_mfma_f32_16x16x32_bf16 v[36:39], v[194:197], v[234:237], v[36:39]
	v_mfma_f32_16x16x32_bf16 v[36:39], v[198:201], v[238:241], v[36:39]
	v_mfma_f32_16x16x32_bf16 v[32:35], v[202:205], v[234:237], v[32:35]
	v_mfma_f32_16x16x32_bf16 v[32:35], v[206:209], v[238:241], v[32:35]
	v_mfma_f32_16x16x32_bf16 v[40:43], v[202:205], v[226:229], v[40:43]
	v_mfma_f32_16x16x32_bf16 v[40:43], v[206:209], v[230:233], v[40:43]
	v_mfma_f32_16x16x32_bf16 v[48:51], v[202:205], v[218:221], v[48:51]
	v_mfma_f32_16x16x32_bf16 v[48:51], v[206:209], v[222:225], v[48:51]
	s_setprio 2
	s_barrier
; #define PG8_STAGE(bufoff, gbase, voff) do { _Pragma("unroll") for (int _i = 0; _i < 2; ++_i) \
;         __builtin_amdgcn_global_load_lds((const unsigned*)((const char*)(gbase) + (voff)[_i]), (PG8_LAS unsigned*)(lds + (bufoff) + ldsw + _i * 8192), 16, 0, 0); } while (0)
; #define PG8_LDA(dst, b, h) do { _Pragma("unroll") for (int m = 0; m < 4; ++m) _Pragma("unroll") for (int k = 0; k < 2; ++k) dst[m][k] = *(const PG8_LAS bf16x8*)(lds + PG8_SA(b, h) + aoff + m * 2048 + k * 1024); } while (0)
; #define PG8_MMA(ai, bj, At, Bt) do { __builtin_amdgcn_s_setprio(1); _Pragma("unroll") for (int m = 0; m < 4; ++m) _Pragma("unroll") for (int n = 0; n < 2; ++n) _Pragma("unroll") for (int k = 0; k < 2; ++k) \
;         acc[ai][bj][m][n] = __builtin_amdgcn_mfma_f32_16x16x32_bf16(Bt[n][k], At[m][k], acc[ai][bj][m][n], 0, 0, 0); __builtin_amdgcn_s_setprio(0); } while (0)
; #define PG8_WAIT_V(n) asm volatile("s_waitcnt vmcnt(" #n ")" ::: "memory")
; #define PG8_WAIT_L(n) asm volatile("s_waitcnt lgkmcnt(" #n ")" ::: "memory")
; #define PG8_BAR __builtin_amdgcn_s_barrier()
; #define PG8_SCHED __builtin_amdgcn_sched_barrier(0)
; template <class Epi, class Sched, bool ALIGN_EPI = false, bool SP2 = false>
; __device__ __forceinline__ void gemm_phase(PG8_LAS unsigned char* lds, const Gemm g, const Sched& S, const Epi& E) {
;     ...
;         for (int t = 0; t < nt; t += 2) {
;     ...
;             PG8_WAIT_V(8); PG8_WAIT_L(0); PG8_BAR; PG8_MMA(0, 0, At, B0); PG8_MMA(0, 1, At, B1); PG8_BAR; PG8_SCHED;
;             PG8_LDA(At, 1, 1); PG8_STAGE(PG8_SB(1, 0), b3, voffB); PG8_STAGE(PG8_SB(1, 1), b3 + hstep, voffB); PG8_STAGE(PG8_SA(1, 0), a3, voffA);
;             PG8_WAIT_V(8); PG8_WAIT_L(0); PG8_BAR; PG8_MMA(1, 0, At, B0); PG8_MMA(1, 1, At, B1); PG8_BAR; PG8_SCHED;
	v_mfma_f32_16x16x32_bf16 v[64:67], v[202:205], v[210:213], v[64:67]
	v_mfma_f32_16x16x32_bf16 v[64:67], v[206:209], v[214:217], v[64:67]
	s_setprio 0
	s_add_i32 s62, s62, s3
	v_lshl_add_u64 v[166:167], v[166:167], 0, s[8:9]
	s_mov_b32 m0, s62
	ds_read_b128 v[210:213], v145 offset:49152
	ds_read_b128 v[214:217], v145 offset:50176
	ds_read_b128 v[218:221], v145 offset:51200
	ds_read_b128 v[222:225], v145 offset:52224
	ds_read_b128 v[226:229], v145 offset:53248
	ds_read_b128 v[230:233], v145 offset:54272
	ds_read_b128 v[234:237], v145 offset:55296
	ds_read_b128 v[238:241], v145 offset:56320
	global_load_lds_dwordx4 v[166:167], off
	s_add_i32 m0, s62, 0x2000
	s_add_u32 s78, s78, 0x80080
	v_lshl_add_u64 v[166:167], v[242:243], 0, s[8:9]
	s_addc_u32 s79, s79, 0
	s_add_i32 s62, s63, s3
	global_load_lds_dwordx4 v[166:167], off
	v_lshl_add_u64 v[166:167], s[78:79], 0, v[130:131]
	s_mov_b32 m0, s62
	s_nop 0
	global_load_lds_dwordx4 v[166:167], off
	v_lshl_add_u64 v[166:167], s[78:79], 0, v[134:135]
	s_add_i32 m0, s62, 0x2000
	s_nop 0
	global_load_lds_dwordx4 v[166:167], off
	v_lshl_add_u64 v[166:167], v[244:245], 0, s[8:9]
	s_mov_b32 m0, s89
	s_nop 0
	global_load_lds_dwordx4 v[166:167], off
	v_lshl_add_u64 v[166:167], v[246:247], 0, s[8:9]
	s_mov_b32 m0, s90
	s_nop 0
	global_load_lds_dwordx4 v[166:167], off
	s_waitcnt vmcnt(8)
	s_waitcnt lgkmcnt(0)
	s_setprio 1
	s_barrier
	v_mfma_f32_16x16x32_bf16 v[92:95], v[178:181], v[210:213], v[92:95]
	v_mfma_f32_16x16x32_bf16 v[92:95], v[182:185], v[214:217], v[92:95]
	v_mfma_f32_16x16x32_bf16 v[84:87], v[178:181], v[218:221], v[84:87]
	v_mfma_f32_16x16x32_bf16 v[84:87], v[182:185], v[222:225], v[84:87]
	v_mfma_f32_16x16x32_bf16 v[76:79], v[178:181], v[226:229], v[76:79]
	v_mfma_f32_16x16x32_bf16 v[76:79], v[182:185], v[230:233], v[76:79]
	v_mfma_f32_16x16x32_bf16 v[60:63], v[178:181], v[234:237], v[60:63]
	v_mfma_f32_16x16x32_bf16 v[60:63], v[182:185], v[238:241], v[60:63]
	v_mfma_f32_16x16x32_bf16 v[56:59], v[186:189], v[234:237], v[56:59]
	v_mfma_f32_16x16x32_bf16 v[56:59], v[190:193], v[238:241], v[56:59]
	v_mfma_f32_16x16x32_bf16 v[72:75], v[186:189], v[226:229], v[72:75]
	v_mfma_f32_16x16x32_bf16 v[72:75], v[190:193], v[230:233], v[72:75]
	v_mfma_f32_16x16x32_bf16 v[80:83], v[186:189], v[218:221], v[80:83]
	v_mfma_f32_16x16x32_bf16 v[80:83], v[190:193], v[222:225], v[80:83]
	v_mfma_f32_16x16x32_bf16 v[88:91], v[186:189], v[210:213], v[88:91]
	v_mfma_f32_16x16x32_bf16 v[88:91], v[190:193], v[214:217], v[88:91]
	v_mfma_f32_16x16x32_bf16 v[28:31], v[194:197], v[210:213], v[28:31]
	v_mfma_f32_16x16x32_bf16 v[28:31], v[198:201], v[214:217], v[28:31]
	v_mfma_f32_16x16x32_bf16 v[20:23], v[194:197], v[218:221], v[20:23]
	v_mfma_f32_16x16x32_bf16 v[20:23], v[198:201], v[222:225], v[20:23]
	v_mfma_f32_16x16x32_bf16 v[12:15], v[194:197], v[226:229], v[12:15]
	v_mfma_f32_16x16x32_bf16 v[12:15], v[198:201], v[230:233], v[12:15]
	v_mfma_f32_16x16x32_bf16 v[4:7], v[194:197], v[234:237], v[4:7]
	v_mfma_f32_16x16x32_bf16 v[4:7], v[198:201], v[238:241], v[4:7]
	v_mfma_f32_16x16x32_bf16 v[0:3], v[202:205], v[234:237], v[0:3]
	v_mfma_f32_16x16x32_bf16 v[0:3], v[206:209], v[238:241], v[0:3]
	v_mfma_f32_16x16x32_bf16 v[8:11], v[202:205], v[226:229], v[8:11]
	v_mfma_f32_16x16x32_bf16 v[8:11], v[206:209], v[230:233], v[8:11]
	v_mfma_f32_16x16x32_bf16 v[16:19], v[202:205], v[218:221], v[16:19]
	v_mfma_f32_16x16x32_bf16 v[16:19], v[206:209], v[222:225], v[16:19]
	s_setprio 2
	s_barrier
	v_mfma_f32_16x16x32_bf16 v[24:27], v[202:205], v[210:213], v[24:27]
	v_mfma_f32_16x16x32_bf16 v[24:27], v[206:209], v[214:217], v[24:27]
	s_setprio 0
	s_add_i32 s75, s75, 2
	s_add_u32 s76, s76, 0x100
	s_addc_u32 s77, s77, 0
	s_add_u32 s57, s57, 0x100
	s_addc_u32 s67, s67, 0
	s_cmp_gt_u32 s75, 29
	s_cbranch_scc0 .LBB0_326
	s_and_b64 vcc, exec, s[20:21]
	s_cbranch_vccz .LBB0_329
	s_barrier

; #define PG8_STAGE(bufoff, gbase, voff) do { _Pragma("unroll") for (int _i = 0; _i < 2; ++_i) \
;         __builtin_amdgcn_global_load_lds((const unsigned*)((const char*)(gbase) + (voff)[_i]), (PG8_LAS unsigned*)(lds + (bufoff) + ldsw + _i * 8192), 16, 0, 0); } while (0)
; #define PG8_LDA(dst, b, h) do { _Pragma("unroll") for (int m = 0; m < 4; ++m) _Pragma("unroll") for (int k = 0; k < 2; ++k) dst[m][k] = *(const PG8_LAS bf16x8*)(lds + PG8_SA(b, h) + aoff + m * 2048 + k * 1024); } while (0)
; #define PG8_LDB(dst, b, h) do { _Pragma("unroll") for (int n = 0; n < 2; ++n) _Pragma("unroll") for (int k = 0; k < 2; ++k) dst[n][k] = *(const PG8_LAS bf16x8*)(lds + PG8_SB(b, h) + boff + n * 2048 + k * 1024); } while (0)
; #define PG8_MMA(ai, bj, At, Bt) do { __builtin_amdgcn_s_setprio(1); _Pragma("unroll") for (int m = 0; m < 4; ++m) _Pragma("unroll") for (int n = 0; n < 2; ++n) _Pragma("unroll") for (int k = 0; k < 2; ++k) \
;         acc[ai][bj][m][n] = __builtin_amdgcn_mfma_f32_16x16x32_bf16(Bt[n][k], At[m][k], acc[ai][bj][m][n], 0, 0, 0); __builtin_amdgcn_s_setprio(0); } while (0)
; #define PG8_WAIT_V(n) asm volatile("s_waitcnt vmcnt(" #n ")" ::: "memory")
; #define PG8_BAR __builtin_amdgcn_s_barrier()
; template <class Epi, class Sched, bool ALIGN_EPI = false, bool SP2 = false>
; __device__ __forceinline__ void gemm_phase(PG8_LAS unsigned char* lds, const Gemm g, const Sched& S, const Epi& E) {
;     ...
;         for (int t = 0; t < nt; t += 2) {
;             const bool last = (t == nt - 2);
;             const char* a1 = cA + (size_t)(t + 1) * kstep;
;             const char* a2 = last ? nA : cA + (size_t)(t + 2) * kstep; const char* b2 = last ? nB : cB + (size_t)(t + 2) * kstep;
;             const char* a3 = a2 + kstep; const char* b3 = b2 + kstep;
;             if (last && has_next) S.a_ready(nxt);
;             if constexpr (SP2) {
;             PG8_LDB(B0, 0, 0); PG8_LDB(B1, 0, 1); PG8_SCHED; PG8_LDA(At, 0, 0); PG8_STAGE(PG8_SA(1, 1), a1 + hstep, voffA);
;             PG8_WAIT_V(8); PG8_WAIT_L(0); PG8_BAR; PG8_MMA(0, 0, At, B0); PG8_MMA(0, 1, At, B1); PG8_BAR; PG8_SCHED;
;             PG8_LDA(At, 0, 1); PG8_STAGE(PG8_SB(0, 0), b2, voffB); PG8_STAGE(PG8_SB(0, 1), b2 + hstep, voffB); PG8_STAGE(PG8_SA(0, 0), a2, voffA);
;             PG8_WAIT_V(8); PG8_WAIT_L(0); PG8_BAR; PG8_MMA(1, 0, At, B0); PG8_MMA(1, 1, At, B1); PG8_BAR; PG8_SCHED;
.LBB0_557:
	ds_read_b128 v[144:147], v155
	ds_read_b128 v[160:163], v155 offset:1024
	ds_read_b128 v[164:167], v155 offset:2048
	ds_read_b128 v[168:171], v155 offset:3072
	ds_read_b128 v[172:175], v156
	ds_read_b128 v[176:179], v156 offset:1024
	ds_read_b128 v[180:183], v156 offset:2048
	ds_read_b128 v[184:187], v156 offset:3072
	s_add_u32 s54, s50, 0xfff80080
	s_addc_u32 s55, s51, -1
	s_cmp_eq_u32 s73, 28
	s_cselect_b32 s57, s10, s55
	s_cselect_b32 s56, s11, s54
	s_cselect_b32 s55, s41, s72
	s_cselect_b32 s54, s43, s49
	v_lshl_add_u64 v[220:221], s[50:51], 0, v[136:137]
	s_add_i32 m0, s33, 0xc000
	ds_read_b128 v[188:191], v157
	ds_read_b128 v[192:195], v157 offset:1024
	ds_read_b128 v[196:199], v157 offset:2048
	ds_read_b128 v[200:203], v157 offset:3072
	ds_read_b128 v[204:207], v157 offset:4096
	ds_read_b128 v[208:211], v157 offset:5120
	ds_read_b128 v[212:215], v157 offset:6144
	ds_read_b128 v[216:219], v157 offset:7168
	global_load_lds_dwordx4 v[220:221], off
	v_lshl_add_u64 v[220:221], s[50:51], 0, v[138:139]
	s_add_i32 m0, s33, 0xe000
	s_nop 0
	global_load_lds_dwordx4 v[220:221], off
	s_waitcnt vmcnt(8)
	s_waitcnt lgkmcnt(0)
	s_setprio 1
	s_barrier
	v_mfma_f32_16x16x32_bf16 v[124:127], v[144:147], v[188:191], v[124:127]
	v_mfma_f32_16x16x32_bf16 v[124:127], v[160:163], v[192:195], v[124:127]
	v_mfma_f32_16x16x32_bf16 v[108:111], v[144:147], v[196:199], v[108:111]
	v_mfma_f32_16x16x32_bf16 v[108:111], v[160:163], v[200:203], v[108:111]
	v_mfma_f32_16x16x32_bf16 v[92:95], v[144:147], v[204:207], v[92:95]
	v_mfma_f32_16x16x32_bf16 v[92:95], v[160:163], v[208:211], v[92:95]
	v_mfma_f32_16x16x32_bf16 v[76:79], v[144:147], v[212:215], v[76:79]
	v_mfma_f32_16x16x32_bf16 v[76:79], v[160:163], v[216:219], v[76:79]
	v_mfma_f32_16x16x32_bf16 v[72:75], v[164:167], v[212:215], v[72:75]
	v_mfma_f32_16x16x32_bf16 v[72:75], v[168:171], v[216:219], v[72:75]
	v_mfma_f32_16x16x32_bf16 v[88:91], v[164:167], v[204:207], v[88:91]
	v_mfma_f32_16x16x32_bf16 v[88:91], v[168:171], v[208:211], v[88:91]
	v_mfma_f32_16x16x32_bf16 v[104:107], v[164:167], v[196:199], v[104:107]
	v_mfma_f32_16x16x32_bf16 v[104:107], v[168:171], v[200:203], v[104:107]
	v_mfma_f32_16x16x32_bf16 v[120:123], v[164:167], v[188:191], v[120:123]
	v_mfma_f32_16x16x32_bf16 v[120:123], v[168:171], v[192:195], v[120:123]
	v_mfma_f32_16x16x32_bf16 v[116:119], v[172:175], v[188:191], v[116:119]
	v_mfma_f32_16x16x32_bf16 v[116:119], v[176:179], v[192:195], v[116:119]
	v_mfma_f32_16x16x32_bf16 v[100:103], v[172:175], v[196:199], v[100:103]
	v_mfma_f32_16x16x32_bf16 v[100:103], v[176:179], v[200:203], v[100:103]
	v_mfma_f32_16x16x32_bf16 v[84:87], v[172:175], v[204:207], v[84:87]
	v_mfma_f32_16x16x32_bf16 v[84:87], v[176:179], v[208:211], v[84:87]
	v_mfma_f32_16x16x32_bf16 v[68:71], v[172:175], v[212:215], v[68:71]
	v_mfma_f32_16x16x32_bf16 v[68:71], v[176:179], v[216:219], v[68:71]
	v_mfma_f32_16x16x32_bf16 v[64:67], v[180:183], v[212:215], v[64:67]
	v_mfma_f32_16x16x32_bf16 v[64:67], v[184:187], v[216:219], v[64:67]
	v_mfma_f32_16x16x32_bf16 v[80:83], v[180:183], v[204:207], v[80:83]
	v_mfma_f32_16x16x32_bf16 v[80:83], v[184:187], v[208:211], v[80:83]
	v_mfma_f32_16x16x32_bf16 v[96:99], v[180:183], v[196:199], v[96:99]
	v_mfma_f32_16x16x32_bf16 v[96:99], v[184:187], v[200:203], v[96:99]
	s_setprio 2
	s_barrier
	v_mfma_f32_16x16x32_bf16 v[112:115], v[180:183], v[188:191], v[112:115]
	v_mfma_f32_16x16x32_bf16 v[112:115], v[184:187], v[192:195], v[112:115]
	s_setprio 0
	s_add_i32 s62, s67, s3
	v_lshl_add_u64 v[220:221], s[54:55], 0, v[130:131]
	s_mov_b32 m0, s62
	ds_read_b128 v[188:191], v157 offset:16384
	ds_read_b128 v[192:195], v157 offset:17408
	ds_read_b128 v[196:199], v157 offset:18432
	ds_read_b128 v[200:203], v157 offset:19456
	ds_read_b128 v[204:207], v157 offset:20480
	ds_read_b128 v[208:211], v157 offset:21504
	ds_read_b128 v[212:215], v157 offset:22528
	ds_read_b128 v[216:219], v157 offset:23552
	global_load_lds_dwordx4 v[220:221], off
	s_add_i32 m0, s62, 0x2000
	s_add_u32 s62, s54, 0x80000
	v_lshl_add_u64 v[222:223], s[54:55], 0, v[134:135]
	s_addc_u32 s63, s55, 0
	s_add_i32 s74, s70, s3
	global_load_lds_dwordx4 v[222:223], off
	v_lshl_add_u64 v[224:225], s[62:63], 0, v[130:131]
	s_mov_b32 m0, s74
	v_lshl_add_u64 v[226:227], s[56:57], 0, v[132:133]
	global_load_lds_dwordx4 v[224:225], off
	v_lshl_add_u64 v[224:225], s[62:63], 0, v[134:135]
	s_add_i32 m0, s74, 0x2000
	s_nop 0
	global_load_lds_dwordx4 v[224:225], off
	v_lshl_add_u64 v[224:225], s[56:57], 0, v[128:129]
	s_mov_b32 m0, s33
	s_nop 0
	global_load_lds_dwordx4 v[224:225], off
	s_mov_b32 m0, s35
	s_nop 0
	global_load_lds_dwordx4 v[226:227], off
	s_waitcnt vmcnt(8)
	s_waitcnt lgkmcnt(0)
	s_setprio 1
	s_barrier
; #define PG8_STAGE(bufoff, gbase, voff) do { _Pragma("unroll") for (int _i = 0; _i < 2; ++_i) \
;         __builtin_amdgcn_global_load_lds((const unsigned*)((const char*)(gbase) + (voff)[_i]), (PG8_LAS unsigned*)(lds + (bufoff) + ldsw + _i * 8192), 16, 0, 0); } while (0)
; #define PG8_LDA(dst, b, h) do { _Pragma("unroll") for (int m = 0; m < 4; ++m) _Pragma("unroll") for (int k = 0; k < 2; ++k) dst[m][k] = *(const PG8_LAS bf16x8*)(lds + PG8_SA(b, h) + aoff + m * 2048 + k * 1024); } while (0)
; #define PG8_LDB(dst, b, h) do { _Pragma("unroll") for (int n = 0; n < 2; ++n) _Pragma("unroll") for (int k = 0; k < 2; ++k) dst[n][k] = *(const PG8_LAS bf16x8*)(lds + PG8_SB(b, h) + boff + n * 2048 + k * 1024); } while (0)
; #define PG8_MMA(ai, bj, At, Bt) do { __builtin_amdgcn_s_setprio(1); _Pragma("unroll") for (int m = 0; m < 4; ++m) _Pragma("unroll") for (int n = 0; n < 2; ++n) _Pragma("unroll") for (int k = 0; k < 2; ++k) \
;         acc[ai][bj][m][n] = __builtin_amdgcn_mfma_f32_16x16x32_bf16(Bt[n][k], At[m][k], acc[ai][bj][m][n], 0, 0, 0); __builtin_amdgcn_s_setprio(0); } while (0)
; #define PG8_WAIT_V(n) asm volatile("s_waitcnt vmcnt(" #n ")" ::: "memory")
; #define PG8_WAIT_L(n) asm volatile("s_waitcnt lgkmcnt(" #n ")" ::: "memory")
; #define PG8_BAR __builtin_amdgcn_s_barrier()
; #define PG8_SCHED __builtin_amdgcn_sched_barrier(0)
; template <class Epi, class Sched, bool ALIGN_EPI = false, bool SP2 = false>
; __device__ __forceinline__ void gemm_phase(PG8_LAS unsigned char* lds, const Gemm g, const Sched& S, const Epi& E) {
;     ...
;             PG8_WAIT_V(8); PG8_WAIT_L(0); PG8_BAR; PG8_MMA(1, 0, At, B0); PG8_MMA(1, 1, At, B1); PG8_BAR; PG8_SCHED;
;             PG8_LDB(B0, 1, 0); PG8_LDB(B1, 1, 1); PG8_SCHED; PG8_LDA(At, 1, 0); PG8_STAGE(PG8_SA(0, 1), a2 + hstep, voffA);
;             PG8_WAIT_V(8); PG8_WAIT_L(0); PG8_BAR; PG8_MMA(0, 0, At, B0); PG8_MMA(0, 1, At, B1); PG8_BAR; PG8_SCHED;
	v_mfma_f32_16x16x32_bf16 v[60:63], v[144:147], v[188:191], v[60:63]
	v_mfma_f32_16x16x32_bf16 v[60:63], v[160:163], v[192:195], v[60:63]
	v_mfma_f32_16x16x32_bf16 v[44:47], v[144:147], v[196:199], v[44:47]
	v_mfma_f32_16x16x32_bf16 v[44:47], v[160:163], v[200:203], v[44:47]
	v_mfma_f32_16x16x32_bf16 v[28:31], v[144:147], v[204:207], v[28:31]
	v_mfma_f32_16x16x32_bf16 v[28:31], v[160:163], v[208:211], v[28:31]
	v_mfma_f32_16x16x32_bf16 v[12:15], v[144:147], v[212:215], v[12:15]
	v_mfma_f32_16x16x32_bf16 v[12:15], v[160:163], v[216:219], v[12:15]
	v_mfma_f32_16x16x32_bf16 v[8:11], v[164:167], v[212:215], v[8:11]
	v_mfma_f32_16x16x32_bf16 v[8:11], v[168:171], v[216:219], v[8:11]
	v_mfma_f32_16x16x32_bf16 v[24:27], v[164:167], v[204:207], v[24:27]
	v_mfma_f32_16x16x32_bf16 v[24:27], v[168:171], v[208:211], v[24:27]
	v_mfma_f32_16x16x32_bf16 v[40:43], v[164:167], v[196:199], v[40:43]
	v_mfma_f32_16x16x32_bf16 v[40:43], v[168:171], v[200:203], v[40:43]
	v_mfma_f32_16x16x32_bf16 v[56:59], v[164:167], v[188:191], v[56:59]
	v_mfma_f32_16x16x32_bf16 v[56:59], v[168:171], v[192:195], v[56:59]
	v_mfma_f32_16x16x32_bf16 v[52:55], v[172:175], v[188:191], v[52:55]
	v_mfma_f32_16x16x32_bf16 v[52:55], v[176:179], v[192:195], v[52:55]
	v_mfma_f32_16x16x32_bf16 v[36:39], v[172:175], v[196:199], v[36:39]
	v_mfma_f32_16x16x32_bf16 v[36:39], v[176:179], v[200:203], v[36:39]
	v_mfma_f32_16x16x32_bf16 v[20:23], v[172:175], v[204:207], v[20:23]
	v_mfma_f32_16x16x32_bf16 v[20:23], v[176:179], v[208:211], v[20:23]
	v_mfma_f32_16x16x32_bf16 v[4:7], v[172:175], v[212:215], v[4:7]
	v_mfma_f32_16x16x32_bf16 v[4:7], v[176:179], v[216:219], v[4:7]
	v_mfma_f32_16x16x32_bf16 v[0:3], v[180:183], v[212:215], v[0:3]
	v_mfma_f32_16x16x32_bf16 v[0:3], v[184:187], v[216:219], v[0:3]
	v_mfma_f32_16x16x32_bf16 v[16:19], v[180:183], v[204:207], v[16:19]
	v_mfma_f32_16x16x32_bf16 v[16:19], v[184:187], v[208:211], v[16:19]
	v_mfma_f32_16x16x32_bf16 v[32:35], v[180:183], v[196:199], v[32:35]
	v_mfma_f32_16x16x32_bf16 v[32:35], v[184:187], v[200:203], v[32:35]
	s_setprio 2
	s_barrier
	v_mfma_f32_16x16x32_bf16 v[48:51], v[180:183], v[188:191], v[48:51]
	v_mfma_f32_16x16x32_bf16 v[48:51], v[184:187], v[192:195], v[48:51]
	s_setprio 0
	s_add_i32 s62, 0, 0x18000
	v_add_u32_e32 v159, s62, v153
	s_add_i32 s63, 0, 0x1c000
	ds_read_b128 v[144:147], v159
	ds_read_b128 v[160:163], v159 offset:1024
	ds_read_b128 v[164:167], v159 offset:2048
	ds_read_b128 v[168:171], v159 offset:3072
	v_add_u32_e32 v159, s63, v153
	ds_read_b128 v[172:175], v159
	ds_read_b128 v[176:179], v159 offset:1024
	ds_read_b128 v[180:183], v159 offset:2048
	ds_read_b128 v[184:187], v159 offset:3072
	s_add_u32 s56, s56, 0x80000
	s_addc_u32 s57, s57, 0
	s_mov_b32 m0, s52
	v_lshl_add_u64 v[228:229], s[56:57], 0, v[128:129]
	ds_read_b128 v[188:191], v157 offset:32768
	ds_read_b128 v[192:195], v157 offset:33792
	ds_read_b128 v[196:199], v157 offset:34816
	ds_read_b128 v[200:203], v157 offset:35840
	ds_read_b128 v[204:207], v157 offset:36864
	ds_read_b128 v[208:211], v157 offset:37888
	ds_read_b128 v[212:215], v157 offset:38912
	ds_read_b128 v[216:219], v157 offset:39936
	global_load_lds_dwordx4 v[228:229], off
	v_lshl_add_u64 v[228:229], s[56:57], 0, v[132:133]
	s_mov_b32 m0, s53
	s_nop 0
	global_load_lds_dwordx4 v[228:229], off
	s_waitcnt vmcnt(8)
	s_waitcnt lgkmcnt(0)
	s_setprio 1
	s_barrier
	v_mfma_f32_16x16x32_bf16 v[124:127], v[144:147], v[188:191], v[124:127]
	v_mfma_f32_16x16x32_bf16 v[124:127], v[160:163], v[192:195], v[124:127]
	v_mfma_f32_16x16x32_bf16 v[108:111], v[144:147], v[196:199], v[108:111]
	v_mfma_f32_16x16x32_bf16 v[108:111], v[160:163], v[200:203], v[108:111]
	v_mfma_f32_16x16x32_bf16 v[92:95], v[144:147], v[204:207], v[92:95]
	v_mfma_f32_16x16x32_bf16 v[92:95], v[160:163], v[208:211], v[92:95]
	v_mfma_f32_16x16x32_bf16 v[76:79], v[144:147], v[212:215], v[76:79]
	v_mfma_f32_16x16x32_bf16 v[76:79], v[160:163], v[216:219], v[76:79]
	v_mfma_f32_16x16x32_bf16 v[72:75], v[164:167], v[212:215], v[72:75]
	v_mfma_f32_16x16x32_bf16 v[72:75], v[168:171], v[216:219], v[72:75]
	v_mfma_f32_16x16x32_bf16 v[88:91], v[164:167], v[204:207], v[88:91]
	v_mfma_f32_16x16x32_bf16 v[88:91], v[168:171], v[208:211], v[88:91]
	v_mfma_f32_16x16x32_bf16 v[104:107], v[164:167], v[196:199], v[104:107]
	v_mfma_f32_16x16x32_bf16 v[104:107], v[168:171], v[200:203], v[104:107]
	v_mfma_f32_16x16x32_bf16 v[120:123], v[164:167], v[188:191], v[120:123]
	v_mfma_f32_16x16x32_bf16 v[120:123], v[168:171], v[192:195], v[120:123]
	v_mfma_f32_16x16x32_bf16 v[116:119], v[172:175], v[188:191], v[116:119]
	v_mfma_f32_16x16x32_bf16 v[116:119], v[176:179], v[192:195], v[116:119]
	v_mfma_f32_16x16x32_bf16 v[100:103], v[172:175], v[196:199], v[100:103]
	v_mfma_f32_16x16x32_bf16 v[100:103], v[176:179], v[200:203], v[100:103]
	v_mfma_f32_16x16x32_bf16 v[84:87], v[172:175], v[204:207], v[84:87]
	v_mfma_f32_16x16x32_bf16 v[84:87], v[176:179], v[208:211], v[84:87]
	v_mfma_f32_16x16x32_bf16 v[68:71], v[172:175], v[212:215], v[68:71]
	v_mfma_f32_16x16x32_bf16 v[68:71], v[176:179], v[216:219], v[68:71]
	v_mfma_f32_16x16x32_bf16 v[64:67], v[180:183], v[212:215], v[64:67]
	v_mfma_f32_16x16x32_bf16 v[64:67], v[184:187], v[216:219], v[64:67]
	v_mfma_f32_16x16x32_bf16 v[80:83], v[180:183], v[204:207], v[80:83]
	v_mfma_f32_16x16x32_bf16 v[80:83], v[184:187], v[208:211], v[80:83]
	v_mfma_f32_16x16x32_bf16 v[96:99], v[180:183], v[196:199], v[96:99]
	v_mfma_f32_16x16x32_bf16 v[96:99], v[184:187], v[200:203], v[96:99]
	s_setprio 2
	s_barrier
; #define PG8_STAGE(bufoff, gbase, voff) do { _Pragma("unroll") for (int _i = 0; _i < 2; ++_i) \
;         __builtin_amdgcn_global_load_lds((const unsigned*)((const char*)(gbase) + (voff)[_i]), (PG8_LAS unsigned*)(lds + (bufoff) + ldsw + _i * 8192), 16, 0, 0); } while (0)
; #define PG8_LDA(dst, b, h) do { _Pragma("unroll") for (int m = 0; m < 4; ++m) _Pragma("unroll") for (int k = 0; k < 2; ++k) dst[m][k] = *(const PG8_LAS bf16x8*)(lds + PG8_SA(b, h) + aoff + m * 2048 + k * 1024); } while (0)
; #define PG8_MMA(ai, bj, At, Bt) do { __builtin_amdgcn_s_setprio(1); _Pragma("unroll") for (int m = 0; m < 4; ++m) _Pragma("unroll") for (int n = 0; n < 2; ++n) _Pragma("unroll") for (int k = 0; k < 2; ++k) \
;         acc[ai][bj][m][n] = __builtin_amdgcn_mfma_f32_16x16x32_bf16(Bt[n][k], At[m][k], acc[ai][bj][m][n], 0, 0, 0); __builtin_amdgcn_s_setprio(0); } while (0)
; #define PG8_WAIT_V(n) asm volatile("s_waitcnt vmcnt(" #n ")" ::: "memory")
; #define PG8_WAIT_L(n) asm volatile("s_waitcnt lgkmcnt(" #n ")" ::: "memory")
; #define PG8_BAR __builtin_amdgcn_s_barrier()
; #define PG8_SCHED __builtin_amdgcn_sched_barrier(0)
; template <class Epi, class Sched, bool ALIGN_EPI = false, bool SP2 = false>
; __device__ __forceinline__ void gemm_phase(PG8_LAS unsigned char* lds, const Gemm g, const Sched& S, const Epi& E) {
;     ...
;         for (int t = 0; t < nt; t += 2) {
;     ...
;             PG8_WAIT_V(8); PG8_WAIT_L(0); PG8_BAR; PG8_MMA(0, 0, At, B0); PG8_MMA(0, 1, At, B1); PG8_BAR; PG8_SCHED;
;             PG8_LDA(At, 1, 1); PG8_STAGE(PG8_SB(1, 0), b3, voffB); PG8_STAGE(PG8_SB(1, 1), b3 + hstep, voffB); PG8_STAGE(PG8_SA(1, 0), a3, voffA);
;             PG8_WAIT_V(8); PG8_WAIT_L(0); PG8_BAR; PG8_MMA(1, 0, At, B0); PG8_MMA(1, 1, At, B1); PG8_BAR; PG8_SCHED;
	v_mfma_f32_16x16x32_bf16 v[112:115], v[180:183], v[188:191], v[112:115]
	v_mfma_f32_16x16x32_bf16 v[112:115], v[184:187], v[192:195], v[112:115]
	s_setprio 0
	s_add_i32 s56, s62, s3
	v_lshl_add_u64 v[220:221], v[220:221], 0, s[20:21]
	s_mov_b32 m0, s56
	ds_read_b128 v[188:191], v157 offset:49152
	ds_read_b128 v[192:195], v157 offset:50176
	ds_read_b128 v[196:199], v157 offset:51200
	ds_read_b128 v[200:203], v157 offset:52224
	ds_read_b128 v[204:207], v157 offset:53248
	ds_read_b128 v[208:211], v157 offset:54272
	ds_read_b128 v[212:215], v157 offset:55296
	ds_read_b128 v[216:219], v157 offset:56320
	global_load_lds_dwordx4 v[220:221], off
	s_add_i32 m0, s56, 0x2000
	s_add_u32 s54, s54, 0x80080
	v_lshl_add_u64 v[220:221], v[222:223], 0, s[20:21]
	s_addc_u32 s55, s55, 0
	s_add_i32 s56, s63, s3
	global_load_lds_dwordx4 v[220:221], off
	v_lshl_add_u64 v[220:221], s[54:55], 0, v[130:131]
	s_mov_b32 m0, s56
	s_nop 0
	global_load_lds_dwordx4 v[220:221], off
	v_lshl_add_u64 v[220:221], s[54:55], 0, v[134:135]
	s_add_i32 m0, s56, 0x2000
	s_nop 0
	global_load_lds_dwordx4 v[220:221], off
	v_lshl_add_u64 v[220:221], v[224:225], 0, s[20:21]
	s_mov_b32 m0, s64
	s_nop 0
	global_load_lds_dwordx4 v[220:221], off
	v_lshl_add_u64 v[220:221], v[226:227], 0, s[20:21]
	s_mov_b32 m0, s65
	s_nop 0
	global_load_lds_dwordx4 v[220:221], off
	s_waitcnt vmcnt(8)
	s_waitcnt lgkmcnt(0)
	s_setprio 1
	s_barrier
	v_mfma_f32_16x16x32_bf16 v[60:63], v[144:147], v[188:191], v[60:63]
	v_mfma_f32_16x16x32_bf16 v[60:63], v[160:163], v[192:195], v[60:63]
	v_mfma_f32_16x16x32_bf16 v[44:47], v[144:147], v[196:199], v[44:47]
	v_mfma_f32_16x16x32_bf16 v[44:47], v[160:163], v[200:203], v[44:47]
	v_mfma_f32_16x16x32_bf16 v[28:31], v[144:147], v[204:207], v[28:31]
	v_mfma_f32_16x16x32_bf16 v[28:31], v[160:163], v[208:211], v[28:31]
	v_mfma_f32_16x16x32_bf16 v[12:15], v[144:147], v[212:215], v[12:15]
	v_mfma_f32_16x16x32_bf16 v[12:15], v[160:163], v[216:219], v[12:15]
	v_mfma_f32_16x16x32_bf16 v[8:11], v[164:167], v[212:215], v[8:11]
	v_mfma_f32_16x16x32_bf16 v[8:11], v[168:171], v[216:219], v[8:11]
	v_mfma_f32_16x16x32_bf16 v[24:27], v[164:167], v[204:207], v[24:27]
	v_mfma_f32_16x16x32_bf16 v[24:27], v[168:171], v[208:211], v[24:27]
	v_mfma_f32_16x16x32_bf16 v[40:43], v[164:167], v[196:199], v[40:43]
	v_mfma_f32_16x16x32_bf16 v[40:43], v[168:171], v[200:203], v[40:43]
	v_mfma_f32_16x16x32_bf16 v[56:59], v[164:167], v[188:191], v[56:59]
	v_mfma_f32_16x16x32_bf16 v[56:59], v[168:171], v[192:195], v[56:59]
	v_mfma_f32_16x16x32_bf16 v[52:55], v[172:175], v[188:191], v[52:55]
	v_mfma_f32_16x16x32_bf16 v[52:55], v[176:179], v[192:195], v[52:55]
	v_mfma_f32_16x16x32_bf16 v[36:39], v[172:175], v[196:199], v[36:39]
	v_mfma_f32_16x16x32_bf16 v[36:39], v[176:179], v[200:203], v[36:39]
	v_mfma_f32_16x16x32_bf16 v[20:23], v[172:175], v[204:207], v[20:23]
	v_mfma_f32_16x16x32_bf16 v[20:23], v[176:179], v[208:211], v[20:23]
	v_mfma_f32_16x16x32_bf16 v[4:7], v[172:175], v[212:215], v[4:7]
	v_mfma_f32_16x16x32_bf16 v[4:7], v[176:179], v[216:219], v[4:7]
	v_mfma_f32_16x16x32_bf16 v[0:3], v[180:183], v[212:215], v[0:3]
	v_mfma_f32_16x16x32_bf16 v[0:3], v[184:187], v[216:219], v[0:3]
	v_mfma_f32_16x16x32_bf16 v[16:19], v[180:183], v[204:207], v[16:19]
	v_mfma_f32_16x16x32_bf16 v[16:19], v[184:187], v[208:211], v[16:19]
	v_mfma_f32_16x16x32_bf16 v[32:35], v[180:183], v[196:199], v[32:35]
	v_mfma_f32_16x16x32_bf16 v[32:35], v[184:187], v[200:203], v[32:35]
	s_setprio 2
	s_barrier
	v_mfma_f32_16x16x32_bf16 v[48:51], v[180:183], v[188:191], v[48:51]
	v_mfma_f32_16x16x32_bf16 v[48:51], v[184:187], v[192:195], v[48:51]
	s_setprio 0
	s_add_i32 s73, s73, 2
	s_add_u32 s50, s50, 0x100
	s_addc_u32 s51, s51, 0
	s_add_u32 s49, s49, 0x100
	s_addc_u32 s72, s72, 0
	s_cmp_gt_u32 s73, 29
	s_cbranch_scc0 .LBB0_557
	s_and_b64 vcc, exec, s[38:39]
	s_cbranch_vccz .LBB0_560
	s_barrier

; #define PG8_STAGE(bufoff, gbase, voff) do { _Pragma("unroll") for (int _i = 0; _i < 2; ++_i) \
;         __builtin_amdgcn_global_load_lds((const unsigned*)((const char*)(gbase) + (voff)[_i]), (PG8_LAS unsigned*)(lds + (bufoff) + ldsw + _i * 8192), 16, 0, 0); } while (0)
; #define PG8_LDA(dst, b, h) do { _Pragma("unroll") for (int m = 0; m < 4; ++m) _Pragma("unroll") for (int k = 0; k < 2; ++k) dst[m][k] = *(const PG8_LAS bf16x8*)(lds + PG8_SA(b, h) + aoff + m * 2048 + k * 1024); } while (0)
; #define PG8_LDB(dst, b, h) do { _Pragma("unroll") for (int n = 0; n < 2; ++n) _Pragma("unroll") for (int k = 0; k < 2; ++k) dst[n][k] = *(const PG8_LAS bf16x8*)(lds + PG8_SB(b, h) + boff + n * 2048 + k * 1024); } while (0)
; #define PG8_MMA(ai, bj, At, Bt) do { __builtin_amdgcn_s_setprio(1); _Pragma("unroll") for (int m = 0; m < 4; ++m) _Pragma("unroll") for (int n = 0; n < 2; ++n) _Pragma("unroll") for (int k = 0; k < 2; ++k) \
;         acc[ai][bj][m][n] = __builtin_amdgcn_mfma_f32_16x16x32_bf16(Bt[n][k], At[m][k], acc[ai][bj][m][n], 0, 0, 0); __builtin_amdgcn_s_setprio(0); } while (0)
; #define PG8_WAIT_V(n) asm volatile("s_waitcnt vmcnt(" #n ")" ::: "memory")
; #define PG8_BAR __builtin_amdgcn_s_barrier()
; template <class Epi, class Sched, bool ALIGN_EPI = false, bool SP2 = false>
; __device__ __forceinline__ void gemm_phase(PG8_LAS unsigned char* lds, const Gemm g, const Sched& S, const Epi& E) {
;     ...
;         for (int t = 0; t < nt; t += 2) {
;             const bool last = (t == nt - 2);
;             const char* a1 = cA + (size_t)(t + 1) * kstep;
;             const char* a2 = last ? nA : cA + (size_t)(t + 2) * kstep; const char* b2 = last ? nB : cB + (size_t)(t + 2) * kstep;
;             const char* a3 = a2 + kstep; const char* b3 = b2 + kstep;
;             if (last && has_next) S.a_ready(nxt);
;             if constexpr (SP2) {
;             PG8_LDB(B0, 0, 0); PG8_LDB(B1, 0, 1); PG8_SCHED; PG8_LDA(At, 0, 0); PG8_STAGE(PG8_SA(1, 1), a1 + hstep, voffA);
;             PG8_WAIT_V(8); PG8_WAIT_L(0); PG8_BAR; PG8_MMA(0, 0, At, B0); PG8_MMA(0, 1, At, B1); PG8_BAR; PG8_SCHED;
;             PG8_LDA(At, 0, 1); PG8_STAGE(PG8_SB(0, 0), b2, voffB); PG8_STAGE(PG8_SB(0, 1), b2 + hstep, voffB); PG8_STAGE(PG8_SA(0, 0), a2, voffA);
;             PG8_WAIT_V(8); PG8_WAIT_L(0); PG8_BAR; PG8_MMA(1, 0, At, B0); PG8_MMA(1, 1, At, B1); PG8_BAR; PG8_SCHED;
.LBB0_700:
	ds_read_b128 v[164:167], v155
	ds_read_b128 v[168:171], v155 offset:1024
	ds_read_b128 v[172:175], v155 offset:2048
	ds_read_b128 v[176:179], v155 offset:3072
	ds_read_b128 v[180:183], v157
	ds_read_b128 v[184:187], v157 offset:1024
	ds_read_b128 v[188:191], v157 offset:2048
	ds_read_b128 v[192:195], v157 offset:3072
	s_add_u32 s46, s44, 0xfff80080
	s_addc_u32 s47, s45, -1
	s_cmp_eq_u32 s67, 28
	s_cselect_b32 s49, s10, s47
	s_cselect_b32 s48, s11, s46
	s_cselect_b32 s47, s21, s66
	s_cselect_b32 s46, s37, s65
	v_lshl_add_u64 v[228:229], s[44:45], 0, v[138:139]
	s_add_i32 m0, s43, 0xc000
	ds_read_b128 v[196:199], v159
	ds_read_b128 v[200:203], v159 offset:1024
	ds_read_b128 v[204:207], v159 offset:2048
	ds_read_b128 v[208:211], v159 offset:3072
	ds_read_b128 v[212:215], v159 offset:4096
	ds_read_b128 v[216:219], v159 offset:5120
	ds_read_b128 v[220:223], v159 offset:6144
	ds_read_b128 v[224:227], v159 offset:7168
	global_load_lds_dwordx4 v[228:229], off
	v_lshl_add_u64 v[228:229], s[44:45], 0, v[140:141]
	s_add_i32 m0, s43, 0xe000
	s_nop 0
	global_load_lds_dwordx4 v[228:229], off
	s_waitcnt vmcnt(8)
	s_waitcnt lgkmcnt(0)
	s_setprio 1
	s_barrier
	v_mfma_f32_16x16x32_bf16 v[124:127], v[164:167], v[196:199], v[124:127]
	v_mfma_f32_16x16x32_bf16 v[124:127], v[168:171], v[200:203], v[124:127]
	v_mfma_f32_16x16x32_bf16 v[108:111], v[164:167], v[204:207], v[108:111]
	v_mfma_f32_16x16x32_bf16 v[108:111], v[168:171], v[208:211], v[108:111]
	v_mfma_f32_16x16x32_bf16 v[92:95], v[164:167], v[212:215], v[92:95]
	v_mfma_f32_16x16x32_bf16 v[92:95], v[168:171], v[216:219], v[92:95]
	v_mfma_f32_16x16x32_bf16 v[76:79], v[164:167], v[220:223], v[76:79]
	v_mfma_f32_16x16x32_bf16 v[76:79], v[168:171], v[224:227], v[76:79]
	v_mfma_f32_16x16x32_bf16 v[72:75], v[172:175], v[220:223], v[72:75]
	v_mfma_f32_16x16x32_bf16 v[72:75], v[176:179], v[224:227], v[72:75]
	v_mfma_f32_16x16x32_bf16 v[88:91], v[172:175], v[212:215], v[88:91]
	v_mfma_f32_16x16x32_bf16 v[88:91], v[176:179], v[216:219], v[88:91]
	v_mfma_f32_16x16x32_bf16 v[104:107], v[172:175], v[204:207], v[104:107]
	v_mfma_f32_16x16x32_bf16 v[104:107], v[176:179], v[208:211], v[104:107]
	v_mfma_f32_16x16x32_bf16 v[120:123], v[172:175], v[196:199], v[120:123]
	v_mfma_f32_16x16x32_bf16 v[120:123], v[176:179], v[200:203], v[120:123]
	v_mfma_f32_16x16x32_bf16 v[116:119], v[180:183], v[196:199], v[116:119]
	v_mfma_f32_16x16x32_bf16 v[116:119], v[184:187], v[200:203], v[116:119]
	v_mfma_f32_16x16x32_bf16 v[100:103], v[180:183], v[204:207], v[100:103]
	v_mfma_f32_16x16x32_bf16 v[100:103], v[184:187], v[208:211], v[100:103]
	v_mfma_f32_16x16x32_bf16 v[84:87], v[180:183], v[212:215], v[84:87]
	v_mfma_f32_16x16x32_bf16 v[84:87], v[184:187], v[216:219], v[84:87]
	v_mfma_f32_16x16x32_bf16 v[68:71], v[180:183], v[220:223], v[68:71]
	v_mfma_f32_16x16x32_bf16 v[68:71], v[184:187], v[224:227], v[68:71]
	v_mfma_f32_16x16x32_bf16 v[64:67], v[188:191], v[220:223], v[64:67]
	v_mfma_f32_16x16x32_bf16 v[64:67], v[192:195], v[224:227], v[64:67]
	v_mfma_f32_16x16x32_bf16 v[80:83], v[188:191], v[212:215], v[80:83]
	v_mfma_f32_16x16x32_bf16 v[80:83], v[192:195], v[216:219], v[80:83]
	v_mfma_f32_16x16x32_bf16 v[96:99], v[188:191], v[204:207], v[96:99]
	v_mfma_f32_16x16x32_bf16 v[96:99], v[192:195], v[208:211], v[96:99]
	s_setprio 2
	s_barrier
	v_mfma_f32_16x16x32_bf16 v[112:115], v[188:191], v[196:199], v[112:115]
	v_mfma_f32_16x16x32_bf16 v[112:115], v[192:195], v[200:203], v[112:115]
	s_setprio 0
	s_add_i32 s62, s58, s3
	v_lshl_add_u64 v[228:229], s[46:47], 0, v[130:131]
	s_mov_b32 m0, s62
	ds_read_b128 v[196:199], v159 offset:16384
	ds_read_b128 v[200:203], v159 offset:17408
	ds_read_b128 v[204:207], v159 offset:18432
	ds_read_b128 v[208:211], v159 offset:19456
	ds_read_b128 v[212:215], v159 offset:20480
	ds_read_b128 v[216:219], v159 offset:21504
	ds_read_b128 v[220:223], v159 offset:22528
	ds_read_b128 v[224:227], v159 offset:23552
	global_load_lds_dwordx4 v[228:229], off
	s_add_i32 m0, s62, 0x2000
	s_add_u32 s62, s46, 0x80000
	v_lshl_add_u64 v[230:231], s[46:47], 0, v[134:135]
	s_addc_u32 s63, s47, 0
	s_add_i32 s68, s59, s3
	global_load_lds_dwordx4 v[230:231], off
	v_lshl_add_u64 v[232:233], s[62:63], 0, v[130:131]
	s_mov_b32 m0, s68
	v_lshl_add_u64 v[234:235], s[48:49], 0, v[132:133]
	global_load_lds_dwordx4 v[232:233], off
	v_lshl_add_u64 v[232:233], s[62:63], 0, v[134:135]
	s_add_i32 m0, s68, 0x2000
	s_nop 0
	global_load_lds_dwordx4 v[232:233], off
	v_lshl_add_u64 v[232:233], s[48:49], 0, v[128:129]
	s_mov_b32 m0, s43
	s_nop 0
	global_load_lds_dwordx4 v[232:233], off
	s_mov_b32 m0, s50
	s_nop 0
	global_load_lds_dwordx4 v[234:235], off
	s_waitcnt vmcnt(8)
	s_waitcnt lgkmcnt(0)
	s_setprio 1
	s_barrier
; #define PG8_STAGE(bufoff, gbase, voff) do { _Pragma("unroll") for (int _i = 0; _i < 2; ++_i) \
;         __builtin_amdgcn_global_load_lds((const unsigned*)((const char*)(gbase) + (voff)[_i]), (PG8_LAS unsigned*)(lds + (bufoff) + ldsw + _i * 8192), 16, 0, 0); } while (0)
; #define PG8_LDA(dst, b, h) do { _Pragma("unroll") for (int m = 0; m < 4; ++m) _Pragma("unroll") for (int k = 0; k < 2; ++k) dst[m][k] = *(const PG8_LAS bf16x8*)(lds + PG8_SA(b, h) + aoff + m * 2048 + k * 1024); } while (0)
; #define PG8_LDB(dst, b, h) do { _Pragma("unroll") for (int n = 0; n < 2; ++n) _Pragma("unroll") for (int k = 0; k < 2; ++k) dst[n][k] = *(const PG8_LAS bf16x8*)(lds + PG8_SB(b, h) + boff + n * 2048 + k * 1024); } while (0)
; #define PG8_MMA(ai, bj, At, Bt) do { __builtin_amdgcn_s_setprio(1); _Pragma("unroll") for (int m = 0; m < 4; ++m) _Pragma("unroll") for (int n = 0; n < 2; ++n) _Pragma("unroll") for (int k = 0; k < 2; ++k) \
;         acc[ai][bj][m][n] = __builtin_amdgcn_mfma_f32_16x16x32_bf16(Bt[n][k], At[m][k], acc[ai][bj][m][n], 0, 0, 0); __builtin_amdgcn_s_setprio(0); } while (0)
; #define PG8_WAIT_V(n) asm volatile("s_waitcnt vmcnt(" #n ")" ::: "memory")
; #define PG8_WAIT_L(n) asm volatile("s_waitcnt lgkmcnt(" #n ")" ::: "memory")
; #define PG8_BAR __builtin_amdgcn_s_barrier()
; #define PG8_SCHED __builtin_amdgcn_sched_barrier(0)
; template <class Epi, class Sched, bool ALIGN_EPI = false, bool SP2 = false>
; __device__ __forceinline__ void gemm_phase(PG8_LAS unsigned char* lds, const Gemm g, const Sched& S, const Epi& E) {
;     ...
;             PG8_WAIT_V(8); PG8_WAIT_L(0); PG8_BAR; PG8_MMA(1, 0, At, B0); PG8_MMA(1, 1, At, B1); PG8_BAR; PG8_SCHED;
;             PG8_LDB(B0, 1, 0); PG8_LDB(B1, 1, 1); PG8_SCHED; PG8_LDA(At, 1, 0); PG8_STAGE(PG8_SA(0, 1), a2 + hstep, voffA);
;             PG8_WAIT_V(8); PG8_WAIT_L(0); PG8_BAR; PG8_MMA(0, 0, At, B0); PG8_MMA(0, 1, At, B1); PG8_BAR; PG8_SCHED;
	v_mfma_f32_16x16x32_bf16 v[60:63], v[164:167], v[196:199], v[60:63]
	v_mfma_f32_16x16x32_bf16 v[60:63], v[168:171], v[200:203], v[60:63]
	v_mfma_f32_16x16x32_bf16 v[44:47], v[164:167], v[204:207], v[44:47]
	v_mfma_f32_16x16x32_bf16 v[44:47], v[168:171], v[208:211], v[44:47]
	v_mfma_f32_16x16x32_bf16 v[28:31], v[164:167], v[212:215], v[28:31]
	v_mfma_f32_16x16x32_bf16 v[28:31], v[168:171], v[216:219], v[28:31]
	v_mfma_f32_16x16x32_bf16 v[12:15], v[164:167], v[220:223], v[12:15]
	v_mfma_f32_16x16x32_bf16 v[12:15], v[168:171], v[224:227], v[12:15]
	v_mfma_f32_16x16x32_bf16 v[8:11], v[172:175], v[220:223], v[8:11]
	v_mfma_f32_16x16x32_bf16 v[8:11], v[176:179], v[224:227], v[8:11]
	v_mfma_f32_16x16x32_bf16 v[24:27], v[172:175], v[212:215], v[24:27]
	v_mfma_f32_16x16x32_bf16 v[24:27], v[176:179], v[216:219], v[24:27]
	v_mfma_f32_16x16x32_bf16 v[40:43], v[172:175], v[204:207], v[40:43]
	v_mfma_f32_16x16x32_bf16 v[40:43], v[176:179], v[208:211], v[40:43]
	v_mfma_f32_16x16x32_bf16 v[56:59], v[172:175], v[196:199], v[56:59]
	v_mfma_f32_16x16x32_bf16 v[56:59], v[176:179], v[200:203], v[56:59]
	v_mfma_f32_16x16x32_bf16 v[52:55], v[180:183], v[196:199], v[52:55]
	v_mfma_f32_16x16x32_bf16 v[52:55], v[184:187], v[200:203], v[52:55]
	v_mfma_f32_16x16x32_bf16 v[36:39], v[180:183], v[204:207], v[36:39]
	v_mfma_f32_16x16x32_bf16 v[36:39], v[184:187], v[208:211], v[36:39]
	v_mfma_f32_16x16x32_bf16 v[20:23], v[180:183], v[212:215], v[20:23]
	v_mfma_f32_16x16x32_bf16 v[20:23], v[184:187], v[216:219], v[20:23]
	v_mfma_f32_16x16x32_bf16 v[4:7], v[180:183], v[220:223], v[4:7]
	v_mfma_f32_16x16x32_bf16 v[4:7], v[184:187], v[224:227], v[4:7]
	v_mfma_f32_16x16x32_bf16 v[0:3], v[188:191], v[220:223], v[0:3]
	v_mfma_f32_16x16x32_bf16 v[0:3], v[192:195], v[224:227], v[0:3]
	v_mfma_f32_16x16x32_bf16 v[16:19], v[188:191], v[212:215], v[16:19]
	v_mfma_f32_16x16x32_bf16 v[16:19], v[192:195], v[216:219], v[16:19]
	v_mfma_f32_16x16x32_bf16 v[32:35], v[188:191], v[204:207], v[32:35]
	v_mfma_f32_16x16x32_bf16 v[32:35], v[192:195], v[208:211], v[32:35]
	s_setprio 2
	s_barrier
	v_mfma_f32_16x16x32_bf16 v[48:51], v[188:191], v[196:199], v[48:51]
	v_mfma_f32_16x16x32_bf16 v[48:51], v[192:195], v[200:203], v[48:51]
	s_setprio 0
	s_add_i32 s62, 0, 0x18000
	v_add_u32_e32 v161, s62, v147
	s_add_i32 s63, 0, 0x1c000
	ds_read_b128 v[164:167], v161
	ds_read_b128 v[168:171], v161 offset:1024
	ds_read_b128 v[172:175], v161 offset:2048
	ds_read_b128 v[176:179], v161 offset:3072
	v_add_u32_e32 v161, s63, v147
	ds_read_b128 v[180:183], v161
	ds_read_b128 v[184:187], v161 offset:1024
	ds_read_b128 v[188:191], v161 offset:2048
	ds_read_b128 v[192:195], v161 offset:3072
	s_add_u32 s48, s48, 0x80000
	s_addc_u32 s49, s49, 0
	s_mov_b32 m0, s51
	v_lshl_add_u64 v[236:237], s[48:49], 0, v[128:129]
	ds_read_b128 v[196:199], v159 offset:32768
	ds_read_b128 v[200:203], v159 offset:33792
	ds_read_b128 v[204:207], v159 offset:34816
	ds_read_b128 v[208:211], v159 offset:35840
	ds_read_b128 v[212:215], v159 offset:36864
	ds_read_b128 v[216:219], v159 offset:37888
	ds_read_b128 v[220:223], v159 offset:38912
	ds_read_b128 v[224:227], v159 offset:39936
	global_load_lds_dwordx4 v[236:237], off
	v_lshl_add_u64 v[236:237], s[48:49], 0, v[132:133]
	s_mov_b32 m0, s52
	s_nop 0
	global_load_lds_dwordx4 v[236:237], off
	s_waitcnt vmcnt(8)
	s_waitcnt lgkmcnt(0)
	s_setprio 1
	s_barrier
	v_mfma_f32_16x16x32_bf16 v[124:127], v[164:167], v[196:199], v[124:127]
	v_mfma_f32_16x16x32_bf16 v[124:127], v[168:171], v[200:203], v[124:127]
	v_mfma_f32_16x16x32_bf16 v[108:111], v[164:167], v[204:207], v[108:111]
	v_mfma_f32_16x16x32_bf16 v[108:111], v[168:171], v[208:211], v[108:111]
	v_mfma_f32_16x16x32_bf16 v[92:95], v[164:167], v[212:215], v[92:95]
	v_mfma_f32_16x16x32_bf16 v[92:95], v[168:171], v[216:219], v[92:95]
	v_mfma_f32_16x16x32_bf16 v[76:79], v[164:167], v[220:223], v[76:79]
	v_mfma_f32_16x16x32_bf16 v[76:79], v[168:171], v[224:227], v[76:79]
	v_mfma_f32_16x16x32_bf16 v[72:75], v[172:175], v[220:223], v[72:75]
	v_mfma_f32_16x16x32_bf16 v[72:75], v[176:179], v[224:227], v[72:75]
	v_mfma_f32_16x16x32_bf16 v[88:91], v[172:175], v[212:215], v[88:91]
	v_mfma_f32_16x16x32_bf16 v[88:91], v[176:179], v[216:219], v[88:91]
	v_mfma_f32_16x16x32_bf16 v[104:107], v[172:175], v[204:207], v[104:107]
	v_mfma_f32_16x16x32_bf16 v[104:107], v[176:179], v[208:211], v[104:107]
	v_mfma_f32_16x16x32_bf16 v[120:123], v[172:175], v[196:199], v[120:123]
	v_mfma_f32_16x16x32_bf16 v[120:123], v[176:179], v[200:203], v[120:123]
	v_mfma_f32_16x16x32_bf16 v[116:119], v[180:183], v[196:199], v[116:119]
	v_mfma_f32_16x16x32_bf16 v[116:119], v[184:187], v[200:203], v[116:119]
	v_mfma_f32_16x16x32_bf16 v[100:103], v[180:183], v[204:207], v[100:103]
	v_mfma_f32_16x16x32_bf16 v[100:103], v[184:187], v[208:211], v[100:103]
	v_mfma_f32_16x16x32_bf16 v[84:87], v[180:183], v[212:215], v[84:87]
	v_mfma_f32_16x16x32_bf16 v[84:87], v[184:187], v[216:219], v[84:87]
	v_mfma_f32_16x16x32_bf16 v[68:71], v[180:183], v[220:223], v[68:71]
	v_mfma_f32_16x16x32_bf16 v[68:71], v[184:187], v[224:227], v[68:71]
	v_mfma_f32_16x16x32_bf16 v[64:67], v[188:191], v[220:223], v[64:67]
	v_mfma_f32_16x16x32_bf16 v[64:67], v[192:195], v[224:227], v[64:67]
	v_mfma_f32_16x16x32_bf16 v[80:83], v[188:191], v[212:215], v[80:83]
	v_mfma_f32_16x16x32_bf16 v[80:83], v[192:195], v[216:219], v[80:83]
	v_mfma_f32_16x16x32_bf16 v[96:99], v[188:191], v[204:207], v[96:99]
	v_mfma_f32_16x16x32_bf16 v[96:99], v[192:195], v[208:211], v[96:99]
	s_setprio 2
	s_barrier
; #define PG8_STAGE(bufoff, gbase, voff) do { _Pragma("unroll") for (int _i = 0; _i < 2; ++_i) \
;         __builtin_amdgcn_global_load_lds((const unsigned*)((const char*)(gbase) + (voff)[_i]), (PG8_LAS unsigned*)(lds + (bufoff) + ldsw + _i * 8192), 16, 0, 0); } while (0)
; #define PG8_LDA(dst, b, h) do { _Pragma("unroll") for (int m = 0; m < 4; ++m) _Pragma("unroll") for (int k = 0; k < 2; ++k) dst[m][k] = *(const PG8_LAS bf16x8*)(lds + PG8_SA(b, h) + aoff + m * 2048 + k * 1024); } while (0)
; #define PG8_MMA(ai, bj, At, Bt) do { __builtin_amdgcn_s_setprio(1); _Pragma("unroll") for (int m = 0; m < 4; ++m) _Pragma("unroll") for (int n = 0; n < 2; ++n) _Pragma("unroll") for (int k = 0; k < 2; ++k) \
;         acc[ai][bj][m][n] = __builtin_amdgcn_mfma_f32_16x16x32_bf16(Bt[n][k], At[m][k], acc[ai][bj][m][n], 0, 0, 0); __builtin_amdgcn_s_setprio(0); } while (0)
; #define PG8_WAIT_V(n) asm volatile("s_waitcnt vmcnt(" #n ")" ::: "memory")
; #define PG8_WAIT_L(n) asm volatile("s_waitcnt lgkmcnt(" #n ")" ::: "memory")
; #define PG8_BAR __builtin_amdgcn_s_barrier()
; #define PG8_SCHED __builtin_amdgcn_sched_barrier(0)
; template <class Epi, class Sched, bool ALIGN_EPI = false, bool SP2 = false>
; __device__ __forceinline__ void gemm_phase(PG8_LAS unsigned char* lds, const Gemm g, const Sched& S, const Epi& E) {
;     ...
;         for (int t = 0; t < nt; t += 2) {
;     ...
;             PG8_WAIT_V(8); PG8_WAIT_L(0); PG8_BAR; PG8_MMA(0, 0, At, B0); PG8_MMA(0, 1, At, B1); PG8_BAR; PG8_SCHED;
;             PG8_LDA(At, 1, 1); PG8_STAGE(PG8_SB(1, 0), b3, voffB); PG8_STAGE(PG8_SB(1, 1), b3 + hstep, voffB); PG8_STAGE(PG8_SA(1, 0), a3, voffA);
;             PG8_WAIT_V(8); PG8_WAIT_L(0); PG8_BAR; PG8_MMA(1, 0, At, B0); PG8_MMA(1, 1, At, B1); PG8_BAR; PG8_SCHED;
	v_mfma_f32_16x16x32_bf16 v[112:115], v[188:191], v[196:199], v[112:115]
	v_mfma_f32_16x16x32_bf16 v[112:115], v[192:195], v[200:203], v[112:115]
	s_setprio 0
	s_add_i32 s48, s62, s3
	v_lshl_add_u64 v[228:229], v[228:229], 0, s[8:9]
	s_mov_b32 m0, s48
	ds_read_b128 v[196:199], v159 offset:49152
	ds_read_b128 v[200:203], v159 offset:50176
	ds_read_b128 v[204:207], v159 offset:51200
	ds_read_b128 v[208:211], v159 offset:52224
	ds_read_b128 v[212:215], v159 offset:53248
	ds_read_b128 v[216:219], v159 offset:54272
	ds_read_b128 v[220:223], v159 offset:55296
	ds_read_b128 v[224:227], v159 offset:56320
	global_load_lds_dwordx4 v[228:229], off
	s_add_i32 m0, s48, 0x2000
	s_add_u32 s46, s46, 0x80080
	v_lshl_add_u64 v[228:229], v[230:231], 0, s[8:9]
	s_addc_u32 s47, s47, 0
	s_add_i32 s48, s63, s3
	global_load_lds_dwordx4 v[228:229], off
	v_lshl_add_u64 v[228:229], s[46:47], 0, v[130:131]
	s_mov_b32 m0, s48
	s_nop 0
	global_load_lds_dwordx4 v[228:229], off
	v_lshl_add_u64 v[228:229], s[46:47], 0, v[134:135]
	s_add_i32 m0, s48, 0x2000
	s_nop 0
	global_load_lds_dwordx4 v[228:229], off
	v_lshl_add_u64 v[228:229], v[232:233], 0, s[8:9]
	s_mov_b32 m0, s55
	s_nop 0
	global_load_lds_dwordx4 v[228:229], off
	v_lshl_add_u64 v[228:229], v[234:235], 0, s[8:9]
	s_mov_b32 m0, s56
	s_nop 0
	global_load_lds_dwordx4 v[228:229], off
	s_waitcnt vmcnt(8)
	s_waitcnt lgkmcnt(0)
	s_setprio 1
	s_barrier
	v_mfma_f32_16x16x32_bf16 v[60:63], v[164:167], v[196:199], v[60:63]
	v_mfma_f32_16x16x32_bf16 v[60:63], v[168:171], v[200:203], v[60:63]
	v_mfma_f32_16x16x32_bf16 v[44:47], v[164:167], v[204:207], v[44:47]
	v_mfma_f32_16x16x32_bf16 v[44:47], v[168:171], v[208:211], v[44:47]
	v_mfma_f32_16x16x32_bf16 v[28:31], v[164:167], v[212:215], v[28:31]
	v_mfma_f32_16x16x32_bf16 v[28:31], v[168:171], v[216:219], v[28:31]
	v_mfma_f32_16x16x32_bf16 v[12:15], v[164:167], v[220:223], v[12:15]
	v_mfma_f32_16x16x32_bf16 v[12:15], v[168:171], v[224:227], v[12:15]
	v_mfma_f32_16x16x32_bf16 v[8:11], v[172:175], v[220:223], v[8:11]
	v_mfma_f32_16x16x32_bf16 v[8:11], v[176:179], v[224:227], v[8:11]
	v_mfma_f32_16x16x32_bf16 v[24:27], v[172:175], v[212:215], v[24:27]
	v_mfma_f32_16x16x32_bf16 v[24:27], v[176:179], v[216:219], v[24:27]
	v_mfma_f32_16x16x32_bf16 v[40:43], v[172:175], v[204:207], v[40:43]
	v_mfma_f32_16x16x32_bf16 v[40:43], v[176:179], v[208:211], v[40:43]
	v_mfma_f32_16x16x32_bf16 v[56:59], v[172:175], v[196:199], v[56:59]
	v_mfma_f32_16x16x32_bf16 v[56:59], v[176:179], v[200:203], v[56:59]
	v_mfma_f32_16x16x32_bf16 v[52:55], v[180:183], v[196:199], v[52:55]
	v_mfma_f32_16x16x32_bf16 v[52:55], v[184:187], v[200:203], v[52:55]
	v_mfma_f32_16x16x32_bf16 v[36:39], v[180:183], v[204:207], v[36:39]
	v_mfma_f32_16x16x32_bf16 v[36:39], v[184:187], v[208:211], v[36:39]
	v_mfma_f32_16x16x32_bf16 v[20:23], v[180:183], v[212:215], v[20:23]
	v_mfma_f32_16x16x32_bf16 v[20:23], v[184:187], v[216:219], v[20:23]
	v_mfma_f32_16x16x32_bf16 v[4:7], v[180:183], v[220:223], v[4:7]
	v_mfma_f32_16x16x32_bf16 v[4:7], v[184:187], v[224:227], v[4:7]
	v_mfma_f32_16x16x32_bf16 v[0:3], v[188:191], v[220:223], v[0:3]
	v_mfma_f32_16x16x32_bf16 v[0:3], v[192:195], v[224:227], v[0:3]
	v_mfma_f32_16x16x32_bf16 v[16:19], v[188:191], v[212:215], v[16:19]
	v_mfma_f32_16x16x32_bf16 v[16:19], v[192:195], v[216:219], v[16:19]
	v_mfma_f32_16x16x32_bf16 v[32:35], v[188:191], v[204:207], v[32:35]
	v_mfma_f32_16x16x32_bf16 v[32:35], v[192:195], v[208:211], v[32:35]
	s_setprio 2
	s_barrier
	v_mfma_f32_16x16x32_bf16 v[48:51], v[188:191], v[196:199], v[48:51]
	v_mfma_f32_16x16x32_bf16 v[48:51], v[192:195], v[200:203], v[48:51]
	s_setprio 0
	s_add_i32 s67, s67, 2
	s_add_u32 s44, s44, 0x100
	s_addc_u32 s45, s45, 0
	s_add_u32 s65, s65, 0x100
	s_addc_u32 s66, s66, 0
	s_cmp_gt_u32 s67, 29
	s_cbranch_scc0 .LBB0_700
	s_and_b64 vcc, exec, s[12:13]
	s_cbranch_vccz .LBB0_703
	s_barrier

; #define PG8_STAGE(bufoff, gbase, voff) do { _Pragma("unroll") for (int _i = 0; _i < 2; ++_i) \
;         __builtin_amdgcn_global_load_lds((const unsigned*)((const char*)(gbase) + (voff)[_i]), (PG8_LAS unsigned*)(lds + (bufoff) + ldsw + _i * 8192), 16, 0, 0); } while (0)
; #define PG8_LDA(dst, b, h) do { _Pragma("unroll") for (int m = 0; m < 4; ++m) _Pragma("unroll") for (int k = 0; k < 2; ++k) dst[m][k] = *(const PG8_LAS bf16x8*)(lds + PG8_SA(b, h) + aoff + m * 2048 + k * 1024); } while (0)
; #define PG8_LDB(dst, b, h) do { _Pragma("unroll") for (int n = 0; n < 2; ++n) _Pragma("unroll") for (int k = 0; k < 2; ++k) dst[n][k] = *(const PG8_LAS bf16x8*)(lds + PG8_SB(b, h) + boff + n * 2048 + k * 1024); } while (0)
; #define PG8_MMA(ai, bj, At, Bt) do { __builtin_amdgcn_s_setprio(1); _Pragma("unroll") for (int m = 0; m < 4; ++m) _Pragma("unroll") for (int n = 0; n < 2; ++n) _Pragma("unroll") for (int k = 0; k < 2; ++k) \
;         acc[ai][bj][m][n] = __builtin_amdgcn_mfma_f32_16x16x32_bf16(Bt[n][k], At[m][k], acc[ai][bj][m][n], 0, 0, 0); __builtin_amdgcn_s_setprio(0); } while (0)
; #define PG8_WAIT_V(n) asm volatile("s_waitcnt vmcnt(" #n ")" ::: "memory")
; #define PG8_BAR __builtin_amdgcn_s_barrier()
; template <class Epi, class Sched, bool ALIGN_EPI = false, bool SP2 = false>
; __device__ __forceinline__ void gemm_phase(PG8_LAS unsigned char* lds, const Gemm g, const Sched& S, const Epi& E) {
;     ...
;         for (int t = 0; t < nt; t += 2) {
;             const bool last = (t == nt - 2);
;             const char* a1 = cA + (size_t)(t + 1) * kstep;
;             const char* a2 = last ? nA : cA + (size_t)(t + 2) * kstep; const char* b2 = last ? nB : cB + (size_t)(t + 2) * kstep;
;             const char* a3 = a2 + kstep; const char* b3 = b2 + kstep;
;             if (last && has_next) S.a_ready(nxt);
;             if constexpr (SP2) {
;             PG8_LDB(B0, 0, 0); PG8_LDB(B1, 0, 1); PG8_SCHED; PG8_LDA(At, 0, 0); PG8_STAGE(PG8_SA(1, 1), a1 + hstep, voffA);
;             PG8_WAIT_V(8); PG8_WAIT_L(0); PG8_BAR; PG8_MMA(0, 0, At, B0); PG8_MMA(0, 1, At, B1); PG8_BAR; PG8_SCHED;
;             PG8_LDA(At, 0, 1); PG8_STAGE(PG8_SB(0, 0), b2, voffB); PG8_STAGE(PG8_SB(0, 1), b2 + hstep, voffB); PG8_STAGE(PG8_SA(0, 0), a2, voffA);
;             PG8_WAIT_V(8); PG8_WAIT_L(0); PG8_BAR; PG8_MMA(1, 0, At, B0); PG8_MMA(1, 1, At, B1); PG8_BAR; PG8_SCHED;
.LBB0_779:
	ds_read_b128 v[144:147], v155
	ds_read_b128 v[160:163], v155 offset:1024
	ds_read_b128 v[164:167], v155 offset:2048
	ds_read_b128 v[168:171], v155 offset:3072
	ds_read_b128 v[172:175], v156
	ds_read_b128 v[176:179], v156 offset:1024
	ds_read_b128 v[180:183], v156 offset:2048
	ds_read_b128 v[184:187], v156 offset:3072
	s_add_u32 s40, s38, 0xffea0080
	s_addc_u32 s41, s39, -1
	s_cmpk_eq_i32 s58, 0x54
	s_cselect_b32 s43, s7, s41
	s_cselect_b32 s42, s6, s40
	s_cselect_b32 s41, s37, s57
	s_cselect_b32 s40, s36, s11
	v_lshl_add_u64 v[220:221], s[38:39], 0, v[136:137]
	s_add_i32 m0, s33, 0xc000
	ds_read_b128 v[188:191], v157
	ds_read_b128 v[192:195], v157 offset:1024
	ds_read_b128 v[196:199], v157 offset:2048
	ds_read_b128 v[200:203], v157 offset:3072
	ds_read_b128 v[204:207], v157 offset:4096
	ds_read_b128 v[208:211], v157 offset:5120
	ds_read_b128 v[212:215], v157 offset:6144
	ds_read_b128 v[216:219], v157 offset:7168
	global_load_lds_dwordx4 v[220:221], off
	v_lshl_add_u64 v[220:221], s[38:39], 0, v[138:139]
	s_add_i32 m0, s33, 0xe000
	s_nop 0
	global_load_lds_dwordx4 v[220:221], off
	s_waitcnt vmcnt(8)
	s_waitcnt lgkmcnt(0)
	s_setprio 1
	s_barrier
	v_mfma_f32_16x16x32_bf16 v[124:127], v[144:147], v[188:191], v[124:127]
	v_mfma_f32_16x16x32_bf16 v[124:127], v[160:163], v[192:195], v[124:127]
	v_mfma_f32_16x16x32_bf16 v[108:111], v[144:147], v[196:199], v[108:111]
	v_mfma_f32_16x16x32_bf16 v[108:111], v[160:163], v[200:203], v[108:111]
	v_mfma_f32_16x16x32_bf16 v[92:95], v[144:147], v[204:207], v[92:95]
	v_mfma_f32_16x16x32_bf16 v[92:95], v[160:163], v[208:211], v[92:95]
	v_mfma_f32_16x16x32_bf16 v[76:79], v[144:147], v[212:215], v[76:79]
	v_mfma_f32_16x16x32_bf16 v[76:79], v[160:163], v[216:219], v[76:79]
	v_mfma_f32_16x16x32_bf16 v[72:75], v[164:167], v[212:215], v[72:75]
	v_mfma_f32_16x16x32_bf16 v[72:75], v[168:171], v[216:219], v[72:75]
	v_mfma_f32_16x16x32_bf16 v[88:91], v[164:167], v[204:207], v[88:91]
	v_mfma_f32_16x16x32_bf16 v[88:91], v[168:171], v[208:211], v[88:91]
	v_mfma_f32_16x16x32_bf16 v[104:107], v[164:167], v[196:199], v[104:107]
	v_mfma_f32_16x16x32_bf16 v[104:107], v[168:171], v[200:203], v[104:107]
	v_mfma_f32_16x16x32_bf16 v[120:123], v[164:167], v[188:191], v[120:123]
	v_mfma_f32_16x16x32_bf16 v[120:123], v[168:171], v[192:195], v[120:123]
	v_mfma_f32_16x16x32_bf16 v[116:119], v[172:175], v[188:191], v[116:119]
	v_mfma_f32_16x16x32_bf16 v[116:119], v[176:179], v[192:195], v[116:119]
	v_mfma_f32_16x16x32_bf16 v[100:103], v[172:175], v[196:199], v[100:103]
	v_mfma_f32_16x16x32_bf16 v[100:103], v[176:179], v[200:203], v[100:103]
	v_mfma_f32_16x16x32_bf16 v[84:87], v[172:175], v[204:207], v[84:87]
	v_mfma_f32_16x16x32_bf16 v[84:87], v[176:179], v[208:211], v[84:87]
	v_mfma_f32_16x16x32_bf16 v[68:71], v[172:175], v[212:215], v[68:71]
	v_mfma_f32_16x16x32_bf16 v[68:71], v[176:179], v[216:219], v[68:71]
	v_mfma_f32_16x16x32_bf16 v[64:67], v[180:183], v[212:215], v[64:67]
	v_mfma_f32_16x16x32_bf16 v[64:67], v[184:187], v[216:219], v[64:67]
	v_mfma_f32_16x16x32_bf16 v[80:83], v[180:183], v[204:207], v[80:83]
	v_mfma_f32_16x16x32_bf16 v[80:83], v[184:187], v[208:211], v[80:83]
	v_mfma_f32_16x16x32_bf16 v[96:99], v[180:183], v[196:199], v[96:99]
	v_mfma_f32_16x16x32_bf16 v[96:99], v[184:187], v[200:203], v[96:99]
	s_setprio 2
	s_barrier
	v_mfma_f32_16x16x32_bf16 v[112:115], v[180:183], v[188:191], v[112:115]
	v_mfma_f32_16x16x32_bf16 v[112:115], v[184:187], v[192:195], v[112:115]
	s_setprio 0
	s_add_i32 s59, s52, s3
	v_lshl_add_u64 v[220:221], s[40:41], 0, v[130:131]
	s_mov_b32 m0, s59
	ds_read_b128 v[188:191], v157 offset:16384
	ds_read_b128 v[192:195], v157 offset:17408
	ds_read_b128 v[196:199], v157 offset:18432
	ds_read_b128 v[200:203], v157 offset:19456
	ds_read_b128 v[204:207], v157 offset:20480
	ds_read_b128 v[208:211], v157 offset:21504
	ds_read_b128 v[212:215], v157 offset:22528
	ds_read_b128 v[216:219], v157 offset:23552
	global_load_lds_dwordx4 v[220:221], off
	s_add_i32 m0, s59, 0x2000
	s_add_u32 s62, s40, 0x160000
	v_lshl_add_u64 v[222:223], s[40:41], 0, v[134:135]
	s_addc_u32 s63, s41, 0
	s_add_i32 s59, s53, s3
	global_load_lds_dwordx4 v[222:223], off
	v_lshl_add_u64 v[224:225], s[62:63], 0, v[130:131]
	s_mov_b32 m0, s59
	v_lshl_add_u64 v[226:227], s[42:43], 0, v[132:133]
	global_load_lds_dwordx4 v[224:225], off
	v_lshl_add_u64 v[224:225], s[62:63], 0, v[134:135]
	s_add_i32 m0, s59, 0x2000
	s_nop 0
	global_load_lds_dwordx4 v[224:225], off
	v_lshl_add_u64 v[224:225], s[42:43], 0, v[128:129]
	s_mov_b32 m0, s33
	s_nop 0
	global_load_lds_dwordx4 v[224:225], off
	s_mov_b32 m0, s35
	s_nop 0
	global_load_lds_dwordx4 v[226:227], off
	s_waitcnt vmcnt(8)
	s_waitcnt lgkmcnt(0)
	s_setprio 1
	s_barrier
; #define PG8_STAGE(bufoff, gbase, voff) do { _Pragma("unroll") for (int _i = 0; _i < 2; ++_i) \
;         __builtin_amdgcn_global_load_lds((const unsigned*)((const char*)(gbase) + (voff)[_i]), (PG8_LAS unsigned*)(lds + (bufoff) + ldsw + _i * 8192), 16, 0, 0); } while (0)
; #define PG8_LDA(dst, b, h) do { _Pragma("unroll") for (int m = 0; m < 4; ++m) _Pragma("unroll") for (int k = 0; k < 2; ++k) dst[m][k] = *(const PG8_LAS bf16x8*)(lds + PG8_SA(b, h) + aoff + m * 2048 + k * 1024); } while (0)
; #define PG8_LDB(dst, b, h) do { _Pragma("unroll") for (int n = 0; n < 2; ++n) _Pragma("unroll") for (int k = 0; k < 2; ++k) dst[n][k] = *(const PG8_LAS bf16x8*)(lds + PG8_SB(b, h) + boff + n * 2048 + k * 1024); } while (0)
; #define PG8_MMA(ai, bj, At, Bt) do { __builtin_amdgcn_s_setprio(1); _Pragma("unroll") for (int m = 0; m < 4; ++m) _Pragma("unroll") for (int n = 0; n < 2; ++n) _Pragma("unroll") for (int k = 0; k < 2; ++k) \
;         acc[ai][bj][m][n] = __builtin_amdgcn_mfma_f32_16x16x32_bf16(Bt[n][k], At[m][k], acc[ai][bj][m][n], 0, 0, 0); __builtin_amdgcn_s_setprio(0); } while (0)
; #define PG8_WAIT_V(n) asm volatile("s_waitcnt vmcnt(" #n ")" ::: "memory")
; #define PG8_WAIT_L(n) asm volatile("s_waitcnt lgkmcnt(" #n ")" ::: "memory")
; #define PG8_BAR __builtin_amdgcn_s_barrier()
; #define PG8_SCHED __builtin_amdgcn_sched_barrier(0)
; template <class Epi, class Sched, bool ALIGN_EPI = false, bool SP2 = false>
; __device__ __forceinline__ void gemm_phase(PG8_LAS unsigned char* lds, const Gemm g, const Sched& S, const Epi& E) {
;     ...
;             PG8_WAIT_V(8); PG8_WAIT_L(0); PG8_BAR; PG8_MMA(1, 0, At, B0); PG8_MMA(1, 1, At, B1); PG8_BAR; PG8_SCHED;
;             PG8_LDB(B0, 1, 0); PG8_LDB(B1, 1, 1); PG8_SCHED; PG8_LDA(At, 1, 0); PG8_STAGE(PG8_SA(0, 1), a2 + hstep, voffA);
;             PG8_WAIT_V(8); PG8_WAIT_L(0); PG8_BAR; PG8_MMA(0, 0, At, B0); PG8_MMA(0, 1, At, B1); PG8_BAR; PG8_SCHED;
	v_mfma_f32_16x16x32_bf16 v[60:63], v[144:147], v[188:191], v[60:63]
	v_mfma_f32_16x16x32_bf16 v[60:63], v[160:163], v[192:195], v[60:63]
	v_mfma_f32_16x16x32_bf16 v[44:47], v[144:147], v[196:199], v[44:47]
	v_mfma_f32_16x16x32_bf16 v[44:47], v[160:163], v[200:203], v[44:47]
	v_mfma_f32_16x16x32_bf16 v[28:31], v[144:147], v[204:207], v[28:31]
	v_mfma_f32_16x16x32_bf16 v[28:31], v[160:163], v[208:211], v[28:31]
	v_mfma_f32_16x16x32_bf16 v[12:15], v[144:147], v[212:215], v[12:15]
	v_mfma_f32_16x16x32_bf16 v[12:15], v[160:163], v[216:219], v[12:15]
	v_mfma_f32_16x16x32_bf16 v[8:11], v[164:167], v[212:215], v[8:11]
	v_mfma_f32_16x16x32_bf16 v[8:11], v[168:171], v[216:219], v[8:11]
	v_mfma_f32_16x16x32_bf16 v[24:27], v[164:167], v[204:207], v[24:27]
	v_mfma_f32_16x16x32_bf16 v[24:27], v[168:171], v[208:211], v[24:27]
	v_mfma_f32_16x16x32_bf16 v[40:43], v[164:167], v[196:199], v[40:43]
	v_mfma_f32_16x16x32_bf16 v[40:43], v[168:171], v[200:203], v[40:43]
	v_mfma_f32_16x16x32_bf16 v[56:59], v[164:167], v[188:191], v[56:59]
	v_mfma_f32_16x16x32_bf16 v[56:59], v[168:171], v[192:195], v[56:59]
	v_mfma_f32_16x16x32_bf16 v[52:55], v[172:175], v[188:191], v[52:55]
	v_mfma_f32_16x16x32_bf16 v[52:55], v[176:179], v[192:195], v[52:55]
	v_mfma_f32_16x16x32_bf16 v[36:39], v[172:175], v[196:199], v[36:39]
	v_mfma_f32_16x16x32_bf16 v[36:39], v[176:179], v[200:203], v[36:39]
	v_mfma_f32_16x16x32_bf16 v[20:23], v[172:175], v[204:207], v[20:23]
	v_mfma_f32_16x16x32_bf16 v[20:23], v[176:179], v[208:211], v[20:23]
	v_mfma_f32_16x16x32_bf16 v[4:7], v[172:175], v[212:215], v[4:7]
	v_mfma_f32_16x16x32_bf16 v[4:7], v[176:179], v[216:219], v[4:7]
	v_mfma_f32_16x16x32_bf16 v[0:3], v[180:183], v[212:215], v[0:3]
	v_mfma_f32_16x16x32_bf16 v[0:3], v[184:187], v[216:219], v[0:3]
	v_mfma_f32_16x16x32_bf16 v[16:19], v[180:183], v[204:207], v[16:19]
	v_mfma_f32_16x16x32_bf16 v[16:19], v[184:187], v[208:211], v[16:19]
	v_mfma_f32_16x16x32_bf16 v[32:35], v[180:183], v[196:199], v[32:35]
	v_mfma_f32_16x16x32_bf16 v[32:35], v[184:187], v[200:203], v[32:35]
	s_setprio 2
	s_barrier
	v_mfma_f32_16x16x32_bf16 v[48:51], v[180:183], v[188:191], v[48:51]
	v_mfma_f32_16x16x32_bf16 v[48:51], v[184:187], v[192:195], v[48:51]
	s_setprio 0
	s_add_i32 s59, 0, 0x18000
	v_add_u32_e32 v159, s59, v153
	s_add_i32 s61, 0, 0x1c000
	ds_read_b128 v[144:147], v159
	ds_read_b128 v[160:163], v159 offset:1024
	ds_read_b128 v[164:167], v159 offset:2048
	ds_read_b128 v[168:171], v159 offset:3072
	v_add_u32_e32 v159, s61, v153
	ds_read_b128 v[172:175], v159
	ds_read_b128 v[176:179], v159 offset:1024
	ds_read_b128 v[180:183], v159 offset:2048
	ds_read_b128 v[184:187], v159 offset:3072
	s_add_u32 s42, s42, 0x160000
	s_addc_u32 s43, s43, 0
	s_mov_b32 m0, s44
	v_lshl_add_u64 v[228:229], s[42:43], 0, v[128:129]
	ds_read_b128 v[188:191], v157 offset:32768
	ds_read_b128 v[192:195], v157 offset:33792
	ds_read_b128 v[196:199], v157 offset:34816
	ds_read_b128 v[200:203], v157 offset:35840
	ds_read_b128 v[204:207], v157 offset:36864
	ds_read_b128 v[208:211], v157 offset:37888
	ds_read_b128 v[212:215], v157 offset:38912
	ds_read_b128 v[216:219], v157 offset:39936
	global_load_lds_dwordx4 v[228:229], off
	v_lshl_add_u64 v[228:229], s[42:43], 0, v[132:133]
	s_mov_b32 m0, s45
	s_nop 0
	global_load_lds_dwordx4 v[228:229], off
	s_waitcnt vmcnt(8)
	s_waitcnt lgkmcnt(0)
	s_setprio 1
	s_barrier
	v_mfma_f32_16x16x32_bf16 v[124:127], v[144:147], v[188:191], v[124:127]
	v_mfma_f32_16x16x32_bf16 v[124:127], v[160:163], v[192:195], v[124:127]
	v_mfma_f32_16x16x32_bf16 v[108:111], v[144:147], v[196:199], v[108:111]
	v_mfma_f32_16x16x32_bf16 v[108:111], v[160:163], v[200:203], v[108:111]
	v_mfma_f32_16x16x32_bf16 v[92:95], v[144:147], v[204:207], v[92:95]
	v_mfma_f32_16x16x32_bf16 v[92:95], v[160:163], v[208:211], v[92:95]
	v_mfma_f32_16x16x32_bf16 v[76:79], v[144:147], v[212:215], v[76:79]
	v_mfma_f32_16x16x32_bf16 v[76:79], v[160:163], v[216:219], v[76:79]
	v_mfma_f32_16x16x32_bf16 v[72:75], v[164:167], v[212:215], v[72:75]
	v_mfma_f32_16x16x32_bf16 v[72:75], v[168:171], v[216:219], v[72:75]
	v_mfma_f32_16x16x32_bf16 v[88:91], v[164:167], v[204:207], v[88:91]
	v_mfma_f32_16x16x32_bf16 v[88:91], v[168:171], v[208:211], v[88:91]
	v_mfma_f32_16x16x32_bf16 v[104:107], v[164:167], v[196:199], v[104:107]
	v_mfma_f32_16x16x32_bf16 v[104:107], v[168:171], v[200:203], v[104:107]
	v_mfma_f32_16x16x32_bf16 v[120:123], v[164:167], v[188:191], v[120:123]
	v_mfma_f32_16x16x32_bf16 v[120:123], v[168:171], v[192:195], v[120:123]
	v_mfma_f32_16x16x32_bf16 v[116:119], v[172:175], v[188:191], v[116:119]
	v_mfma_f32_16x16x32_bf16 v[116:119], v[176:179], v[192:195], v[116:119]
	v_mfma_f32_16x16x32_bf16 v[100:103], v[172:175], v[196:199], v[100:103]
	v_mfma_f32_16x16x32_bf16 v[100:103], v[176:179], v[200:203], v[100:103]
	v_mfma_f32_16x16x32_bf16 v[84:87], v[172:175], v[204:207], v[84:87]
	v_mfma_f32_16x16x32_bf16 v[84:87], v[176:179], v[208:211], v[84:87]
	v_mfma_f32_16x16x32_bf16 v[68:71], v[172:175], v[212:215], v[68:71]
	v_mfma_f32_16x16x32_bf16 v[68:71], v[176:179], v[216:219], v[68:71]
	v_mfma_f32_16x16x32_bf16 v[64:67], v[180:183], v[212:215], v[64:67]
	v_mfma_f32_16x16x32_bf16 v[64:67], v[184:187], v[216:219], v[64:67]
	v_mfma_f32_16x16x32_bf16 v[80:83], v[180:183], v[204:207], v[80:83]
	v_mfma_f32_16x16x32_bf16 v[80:83], v[184:187], v[208:211], v[80:83]
	v_mfma_f32_16x16x32_bf16 v[96:99], v[180:183], v[196:199], v[96:99]
	v_mfma_f32_16x16x32_bf16 v[96:99], v[184:187], v[200:203], v[96:99]
	s_setprio 2
	s_barrier
; #define PG8_STAGE(bufoff, gbase, voff) do { _Pragma("unroll") for (int _i = 0; _i < 2; ++_i) \
;         __builtin_amdgcn_global_load_lds((const unsigned*)((const char*)(gbase) + (voff)[_i]), (PG8_LAS unsigned*)(lds + (bufoff) + ldsw + _i * 8192), 16, 0, 0); } while (0)
; #define PG8_LDA(dst, b, h) do { _Pragma("unroll") for (int m = 0; m < 4; ++m) _Pragma("unroll") for (int k = 0; k < 2; ++k) dst[m][k] = *(const PG8_LAS bf16x8*)(lds + PG8_SA(b, h) + aoff + m * 2048 + k * 1024); } while (0)
; #define PG8_MMA(ai, bj, At, Bt) do { __builtin_amdgcn_s_setprio(1); _Pragma("unroll") for (int m = 0; m < 4; ++m) _Pragma("unroll") for (int n = 0; n < 2; ++n) _Pragma("unroll") for (int k = 0; k < 2; ++k) \
;         acc[ai][bj][m][n] = __builtin_amdgcn_mfma_f32_16x16x32_bf16(Bt[n][k], At[m][k], acc[ai][bj][m][n], 0, 0, 0); __builtin_amdgcn_s_setprio(0); } while (0)
; #define PG8_WAIT_V(n) asm volatile("s_waitcnt vmcnt(" #n ")" ::: "memory")
; #define PG8_WAIT_L(n) asm volatile("s_waitcnt lgkmcnt(" #n ")" ::: "memory")
; #define PG8_BAR __builtin_amdgcn_s_barrier()
; #define PG8_SCHED __builtin_amdgcn_sched_barrier(0)
; template <class Epi, class Sched, bool ALIGN_EPI = false, bool SP2 = false>
; __device__ __forceinline__ void gemm_phase(PG8_LAS unsigned char* lds, const Gemm g, const Sched& S, const Epi& E) {
;     ...
;         for (int t = 0; t < nt; t += 2) {
;     ...
;             PG8_WAIT_V(8); PG8_WAIT_L(0); PG8_BAR; PG8_MMA(0, 0, At, B0); PG8_MMA(0, 1, At, B1); PG8_BAR; PG8_SCHED;
;             PG8_LDA(At, 1, 1); PG8_STAGE(PG8_SB(1, 0), b3, voffB); PG8_STAGE(PG8_SB(1, 1), b3 + hstep, voffB); PG8_STAGE(PG8_SA(1, 0), a3, voffA);
;             PG8_WAIT_V(8); PG8_WAIT_L(0); PG8_BAR; PG8_MMA(1, 0, At, B0); PG8_MMA(1, 1, At, B1); PG8_BAR; PG8_SCHED;
	v_mfma_f32_16x16x32_bf16 v[112:115], v[180:183], v[188:191], v[112:115]
	v_mfma_f32_16x16x32_bf16 v[112:115], v[184:187], v[192:195], v[112:115]
	s_setprio 0
	s_add_i32 s42, s59, s3
	v_lshl_add_u64 v[220:221], v[220:221], 0, s[16:17]
	s_mov_b32 m0, s42
	ds_read_b128 v[188:191], v157 offset:49152
	ds_read_b128 v[192:195], v157 offset:50176
	ds_read_b128 v[196:199], v157 offset:51200
	ds_read_b128 v[200:203], v157 offset:52224
	ds_read_b128 v[204:207], v157 offset:53248
	ds_read_b128 v[208:211], v157 offset:54272
	ds_read_b128 v[212:215], v157 offset:55296
	ds_read_b128 v[216:219], v157 offset:56320
	global_load_lds_dwordx4 v[220:221], off
	s_add_i32 m0, s42, 0x2000
	s_add_u32 s40, s40, 0x160080
	v_lshl_add_u64 v[220:221], v[222:223], 0, s[16:17]
	s_addc_u32 s41, s41, 0
	s_add_i32 s42, s61, s3
	global_load_lds_dwordx4 v[220:221], off
	v_lshl_add_u64 v[220:221], s[40:41], 0, v[130:131]
	s_mov_b32 m0, s42
	s_nop 0
	global_load_lds_dwordx4 v[220:221], off
	v_lshl_add_u64 v[220:221], s[40:41], 0, v[134:135]
	s_add_i32 m0, s42, 0x2000
	s_nop 0
	global_load_lds_dwordx4 v[220:221], off
	v_lshl_add_u64 v[220:221], v[224:225], 0, s[16:17]
	s_mov_b32 m0, s49
	s_nop 0
	global_load_lds_dwordx4 v[220:221], off
	v_lshl_add_u64 v[220:221], v[226:227], 0, s[16:17]
	s_mov_b32 m0, s50
	s_nop 0
	global_load_lds_dwordx4 v[220:221], off
	s_waitcnt vmcnt(8)
	s_waitcnt lgkmcnt(0)
	s_setprio 1
	s_barrier
	v_mfma_f32_16x16x32_bf16 v[60:63], v[144:147], v[188:191], v[60:63]
	v_mfma_f32_16x16x32_bf16 v[60:63], v[160:163], v[192:195], v[60:63]
	v_mfma_f32_16x16x32_bf16 v[44:47], v[144:147], v[196:199], v[44:47]
	v_mfma_f32_16x16x32_bf16 v[44:47], v[160:163], v[200:203], v[44:47]
	v_mfma_f32_16x16x32_bf16 v[28:31], v[144:147], v[204:207], v[28:31]
	v_mfma_f32_16x16x32_bf16 v[28:31], v[160:163], v[208:211], v[28:31]
	v_mfma_f32_16x16x32_bf16 v[12:15], v[144:147], v[212:215], v[12:15]
	v_mfma_f32_16x16x32_bf16 v[12:15], v[160:163], v[216:219], v[12:15]
	v_mfma_f32_16x16x32_bf16 v[8:11], v[164:167], v[212:215], v[8:11]
	v_mfma_f32_16x16x32_bf16 v[8:11], v[168:171], v[216:219], v[8:11]
	v_mfma_f32_16x16x32_bf16 v[24:27], v[164:167], v[204:207], v[24:27]
	v_mfma_f32_16x16x32_bf16 v[24:27], v[168:171], v[208:211], v[24:27]
	v_mfma_f32_16x16x32_bf16 v[40:43], v[164:167], v[196:199], v[40:43]
	v_mfma_f32_16x16x32_bf16 v[40:43], v[168:171], v[200:203], v[40:43]
	v_mfma_f32_16x16x32_bf16 v[56:59], v[164:167], v[188:191], v[56:59]
	v_mfma_f32_16x16x32_bf16 v[56:59], v[168:171], v[192:195], v[56:59]
	v_mfma_f32_16x16x32_bf16 v[52:55], v[172:175], v[188:191], v[52:55]
	v_mfma_f32_16x16x32_bf16 v[52:55], v[176:179], v[192:195], v[52:55]
	v_mfma_f32_16x16x32_bf16 v[36:39], v[172:175], v[196:199], v[36:39]
	v_mfma_f32_16x16x32_bf16 v[36:39], v[176:179], v[200:203], v[36:39]
	v_mfma_f32_16x16x32_bf16 v[20:23], v[172:175], v[204:207], v[20:23]
	v_mfma_f32_16x16x32_bf16 v[20:23], v[176:179], v[208:211], v[20:23]
	v_mfma_f32_16x16x32_bf16 v[4:7], v[172:175], v[212:215], v[4:7]
	v_mfma_f32_16x16x32_bf16 v[4:7], v[176:179], v[216:219], v[4:7]
	v_mfma_f32_16x16x32_bf16 v[0:3], v[180:183], v[212:215], v[0:3]
	v_mfma_f32_16x16x32_bf16 v[0:3], v[184:187], v[216:219], v[0:3]
	v_mfma_f32_16x16x32_bf16 v[16:19], v[180:183], v[204:207], v[16:19]
	v_mfma_f32_16x16x32_bf16 v[16:19], v[184:187], v[208:211], v[16:19]
	v_mfma_f32_16x16x32_bf16 v[32:35], v[180:183], v[196:199], v[32:35]
	v_mfma_f32_16x16x32_bf16 v[32:35], v[184:187], v[200:203], v[32:35]
	s_setprio 2
	s_barrier
	v_mfma_f32_16x16x32_bf16 v[48:51], v[180:183], v[188:191], v[48:51]
	v_mfma_f32_16x16x32_bf16 v[48:51], v[184:187], v[192:195], v[48:51]
	s_setprio 0
	s_add_i32 s58, s58, 2
	s_add_u32 s38, s38, 0x100
	s_addc_u32 s39, s39, 0
	s_add_u32 s11, s11, 0x100
	s_addc_u32 s57, s57, 0
	s_cmpk_gt_u32 s58, 0x55
	s_cbranch_scc0 .LBB0_779
	s_and_b64 vcc, exec, s[20:21]
	s_cbranch_vccz .LBB0_782
	s_barrier
